# NA: single max3 chain for the per-tile threshold test (one VALU op fewer per tile)
# baseline (speedup 1.0000x reference)
.Lna_wloop:
	s_sub_i32 s36, s24, s23
	s_cmp_lt_u32 s36, s63
	s_cselect_b64 s[40:41], -1, 0
	s_add_i32 s36, s36, 1
	s_cmp_lt_u32 s36, 8
	s_cselect_b64 s[44:45], -1, 0
	s_sub_i32 s37, s36, s62
	s_cmp_lt_u32 s37, 8
	s_cselect_b64 s[46:47], -1, 0
	s_and_b64 s[48:49], s[44:45], s[64:65]
	s_andn2_b64 s[38:39], s[46:47], s[64:65]
	s_or_b64 s[48:49], s[48:49], s[38:39]
	s_or_b64 s[42:43], s[44:45], s[46:47]
	s_and_b64 s[44:45], s[44:45], s[46:47]
	s_and_b64 s[44:45], s[44:45], s[40:41]
	s_cmp_eq_u64 s[44:45], 0
	s_cbranch_scc1 .Lna_slow_w1
	ds_read_b128 v[146:149], v199 offset:0
	ds_read_b128 v[150:153], v199 offset:32
	ds_read_b128 v[154:157], v199 offset:64
	ds_read_b128 v[158:161], v199 offset:96
	v_add_u32_e32 v210, s25, v208
	v_exp_f32_e32 v66, v66
	v_exp_f32_e32 v67, v67
	v_exp_f32_e32 v68, v68
	v_exp_f32_e32 v69, v69
	v_add_f32_e32 v213, v213, v66
	s_waitcnt lgkmcnt(3)
	v_mfma_f32_32x32x16_bf16 v[34:49], v[146:149], v[98:101], v[114:129]
	ds_read_b64 v[162:163], v201 offset:8704
	ds_read_b64 v[164:165], v201 offset:8720
	v_add_f32_e32 v214, v214, v67
	v_add_f32_e32 v213, v213, v68
	v_add_f32_e32 v214, v214, v69
	v_exp_f32_e32 v70, v70
	v_exp_f32_e32 v71, v71
	v_exp_f32_e32 v72, v72
	s_waitcnt lgkmcnt(4)
	v_mfma_f32_32x32x16_bf16 v[34:49], v[150:153], v[102:105], v[34:49]
	ds_read_b64 v[166:167], v201 offset:13056
	ds_read_b64 v[168:169], v201 offset:13072
	v_exp_f32_e32 v73, v73
	v_add_f32_e32 v213, v213, v70
	v_add_f32_e32 v214, v214, v71
	v_add_f32_e32 v213, v213, v72
	v_add_f32_e32 v214, v214, v73
	v_cvt_pk_bf16_f32 v66, v66, v67
	v_cvt_pk_bf16_f32 v67, v68, v69
	v_cvt_pk_bf16_f32 v68, v70, v71
	s_waitcnt lgkmcnt(5)
	v_mfma_f32_32x32x16_bf16 v[34:49], v[154:157], v[106:109], v[34:49]
	ds_read_b64 v[170:171], v201 offset:8736
	ds_read_b64 v[172:173], v201 offset:8752
	v_cvt_pk_bf16_f32 v69, v72, v73
	v_exp_f32_e32 v74, v74
	v_exp_f32_e32 v75, v75
	v_exp_f32_e32 v76, v76
	v_exp_f32_e32 v77, v77
	s_waitcnt lgkmcnt(6)
	v_mfma_f32_32x32x16_bf16 v[34:49], v[158:161], v[110:113], v[34:49]
	ds_read_b64 v[174:175], v201 offset:13088
	ds_read_b64 v[176:177], v201 offset:13104
	ds_read_b128 v[146:149], v210 offset:0
	ds_read_b128 v[150:153], v210 offset:32
	ds_read_b128 v[154:157], v210 offset:64
	ds_read_b128 v[158:161], v210 offset:96
	v_add_f32_e32 v213, v213, v74
	v_add_f32_e32 v214, v214, v75
	v_add_f32_e32 v213, v213, v76
	v_add_f32_e32 v214, v214, v77
	v_exp_f32_e32 v78, v78
	v_exp_f32_e32 v79, v79
	v_exp_f32_e32 v80, v80
	s_waitcnt lgkmcnt(10)
	v_mfma_f32_32x32x16_bf16 v[2:17], v[162:165], v[66:69], v[2:17]
	v_exp_f32_e32 v81, v81
	v_add_f32_e32 v213, v213, v78
	v_add_f32_e32 v214, v214, v79
	v_add_f32_e32 v213, v213, v80
	v_add_f32_e32 v214, v214, v81
	v_cvt_pk_bf16_f32 v74, v74, v75
	v_cvt_pk_bf16_f32 v75, v76, v77
	s_waitcnt lgkmcnt(8)
	v_mfma_f32_32x32x16_bf16 v[18:33], v[166:169], v[66:69], v[18:33]
	v_cvt_pk_bf16_f32 v76, v78, v79
	v_cvt_pk_bf16_f32 v77, v80, v81
	s_waitcnt lgkmcnt(0)
	v_add_f32_e32 v34, v34, v146
	v_add_f32_e32 v35, v35, v147
	v_add_f32_e32 v36, v36, v148
	v_add_f32_e32 v37, v37, v149
	v_add_f32_e32 v38, v38, v150
	v_add_f32_e32 v39, v39, v151
	v_add_f32_e32 v40, v40, v152
	v_mfma_f32_32x32x16_bf16 v[2:17], v[170:173], v[74:77], v[2:17]
	v_add_f32_e32 v41, v41, v153
	v_add_f32_e32 v42, v42, v154
	v_add_f32_e32 v43, v43, v155
	v_add_f32_e32 v44, v44, v156
	v_add_f32_e32 v45, v45, v157
	v_add_f32_e32 v46, v46, v158
	v_add_f32_e32 v47, v47, v159
	v_add_f32_e32 v48, v48, v160
	v_add_f32_e32 v49, v49, v161
	v_mfma_f32_32x32x16_bf16 v[18:33], v[174:177], v[74:77], v[18:33]
	s_waitcnt vmcnt(2)
	ds_write_b128 v204, v[230:233] offset:9216
	ds_write_b64 v205, v[234:235] offset:0
	ds_write_b64 v205, v[236:237] offset:8
	global_load_dwordx4 v[230:233], v206, s[12:13]
	s_add_i32 s20, s20, 1
	s_add_u32 s12, s12, 0x2000
	s_addc_u32 s13, s13, 0
	s_cmp_eq_u32 s20, s22
	s_cselect_b32 s12, s16, s12
	s_cselect_b32 s13, s17, s13
	global_load_dwordx4 v[234:237], v207, s[14:15]
	s_add_i32 s21, s21, 1
	s_add_u32 s14, s14, 0x80
	s_addc_u32 s15, s15, 0
	s_cmp_eq_u32 s21, s22
	s_cselect_b32 s14, s18, s14
	s_cselect_b32 s15, s19, s15
	v_max3_f32 v216, v34, v35, v36
	v_max3_f32 v216, v216, v37, v38
	v_max3_f32 v216, v216, v39, v40
	v_max3_f32 v216, v216, v41, v42
	v_max3_f32 v216, v216, v43, v44
	v_max3_f32 v216, v216, v45, v46
	v_max3_f32 v216, v216, v47, v48
	v_max_f32_e32 v216, v216, v49
	v_cmp_lt_f32_e32 vcc, 4.0, v216
	s_or_b64 s[28:29], vcc, s[26:27]
	s_cmp_lg_u64 s[28:29], 0
	s_cbranch_scc0 .Lna_nr_w1f
	v_mov_b32_e32 v217, v216
	s_nop 1
	v_permlane32_swap_b32_e32 v216, v217
	v_max_f32_e32 v215, v216, v217
	s_nop 15
	v_max_f32_e32 v216, v215, v220
	v_cmp_lt_f32_e32 vcc, 0xf0c9f2ca, v215
	s_nop 1
	v_cndmask_b32_e32 v216, 0, v216, vcc
	v_exp_f32_e64 v217, -v216
	v_add_f32_e32 v212, v212, v216
	v_and_b32_e32 v217, v217, v221
	v_sub_f32_e32 v34, v34, v216
	v_sub_f32_e32 v35, v35, v216
	v_sub_f32_e32 v36, v36, v216
	v_sub_f32_e32 v37, v37, v216
	v_sub_f32_e32 v38, v38, v216
	v_sub_f32_e32 v39, v39, v216
	v_sub_f32_e32 v40, v40, v216
	v_sub_f32_e32 v41, v41, v216
	v_sub_f32_e32 v42, v42, v216
	v_sub_f32_e32 v43, v43, v216
	v_sub_f32_e32 v44, v44, v216
	v_sub_f32_e32 v45, v45, v216
	v_sub_f32_e32 v46, v46, v216
	v_sub_f32_e32 v47, v47, v216
	v_sub_f32_e32 v48, v48, v216
	v_sub_f32_e32 v49, v49, v216
	v_sub_f32_e32 v114, v114, v216
	v_sub_f32_e32 v115, v115, v216
	v_sub_f32_e32 v116, v116, v216
	v_sub_f32_e32 v117, v117, v216
	v_sub_f32_e32 v118, v118, v216
	v_sub_f32_e32 v119, v119, v216
	v_sub_f32_e32 v120, v120, v216
	v_sub_f32_e32 v121, v121, v216
	v_sub_f32_e32 v122, v122, v216
	v_sub_f32_e32 v123, v123, v216
	v_sub_f32_e32 v124, v124, v216
	v_sub_f32_e32 v125, v125, v216
	v_sub_f32_e32 v126, v126, v216
	v_sub_f32_e32 v127, v127, v216
	v_sub_f32_e32 v128, v128, v216
	v_sub_f32_e32 v129, v129, v216
	v_mul_f32_e32 v213, v213, v217
	v_mul_f32_e32 v214, v214, v217
	v_mul_f32_e32 v2, v2, v217
	v_mul_f32_e32 v3, v3, v217
	v_mul_f32_e32 v4, v4, v217
	v_mul_f32_e32 v5, v5, v217
	v_mul_f32_e32 v6, v6, v217
	v_mul_f32_e32 v7, v7, v217
	v_mul_f32_e32 v8, v8, v217
	v_mul_f32_e32 v9, v9, v217
	v_mul_f32_e32 v10, v10, v217
	v_mul_f32_e32 v11, v11, v217
	v_mul_f32_e32 v12, v12, v217
	v_mul_f32_e32 v13, v13, v217
	v_mul_f32_e32 v14, v14, v217
	v_mul_f32_e32 v15, v15, v217
	v_mul_f32_e32 v16, v16, v217
	v_mul_f32_e32 v17, v17, v217
	v_mul_f32_e32 v18, v18, v217
	v_mul_f32_e32 v19, v19, v217
	v_mul_f32_e32 v20, v20, v217
	v_mul_f32_e32 v21, v21, v217
	v_mul_f32_e32 v22, v22, v217
	v_mul_f32_e32 v23, v23, v217
	v_mul_f32_e32 v24, v24, v217
	v_mul_f32_e32 v25, v25, v217
	v_mul_f32_e32 v26, v26, v217
	v_mul_f32_e32 v27, v27, v217
	v_mul_f32_e32 v28, v28, v217
	v_mul_f32_e32 v29, v29, v217
	v_mul_f32_e32 v30, v30, v217
	v_mul_f32_e32 v31, v31, v217
	v_mul_f32_e32 v32, v32, v217
	v_mul_f32_e32 v33, v33, v217
	v_cndmask_b32_e32 v220, v220, v228, vcc
	v_cndmask_b32_e64 v221, v221, -1, vcc
	s_andn2_b64 s[26:27], s[26:27], vcc

.Lna_sl_a_w1s:
	s_waitcnt lgkmcnt(0)
	s_cmp_eq_u64 s[42:43], 0
	s_cbranch_scc1 .Lna_sl_b_w1s
	ds_read_b128 v[146:149], v199 offset:0
	ds_read_b128 v[150:153], v199 offset:32
	ds_read_b128 v[154:157], v199 offset:64
	ds_read_b128 v[158:161], v199 offset:96
	s_waitcnt lgkmcnt(3)
	v_mfma_f32_32x32x16_bf16 v[34:49], v[146:149], v[98:101], v[114:129]
	s_waitcnt lgkmcnt(2)
	v_mfma_f32_32x32x16_bf16 v[34:49], v[150:153], v[102:105], v[34:49]
	s_waitcnt lgkmcnt(1)
	v_mfma_f32_32x32x16_bf16 v[34:49], v[154:157], v[106:109], v[34:49]
	s_waitcnt lgkmcnt(0)
	v_mfma_f32_32x32x16_bf16 v[34:49], v[158:161], v[110:113], v[34:49]
	v_add_u32_e32 v210, s25, v208
	ds_read_b128 v[146:149], v210 offset:0
	ds_read_b128 v[150:153], v210 offset:32
	ds_read_b128 v[154:157], v210 offset:64
	ds_read_b128 v[158:161], v210 offset:96
	s_waitcnt lgkmcnt(0)
	s_nop 15
	v_add_f32_e32 v34, v34, v146
	v_add_f32_e32 v35, v35, v147
	v_add_f32_e32 v36, v36, v148
	v_add_f32_e32 v37, v37, v149
	v_add_f32_e32 v38, v38, v150
	v_add_f32_e32 v39, v39, v151
	v_add_f32_e32 v40, v40, v152
	v_add_f32_e32 v41, v41, v153
	v_add_f32_e32 v42, v42, v154
	v_add_f32_e32 v43, v43, v155
	v_add_f32_e32 v44, v44, v156
	v_add_f32_e32 v45, v45, v157
	v_add_f32_e32 v46, v46, v158
	v_add_f32_e32 v47, v47, v159
	v_add_f32_e32 v48, v48, v160
	v_add_f32_e32 v49, v49, v161
	v_cndmask_b32_e64 v34, v229, v34, s[48:49]
	v_cndmask_b32_e64 v35, v229, v35, s[48:49]
	v_cndmask_b32_e64 v36, v229, v36, s[48:49]
	v_cndmask_b32_e64 v37, v229, v37, s[48:49]
	v_cndmask_b32_e64 v38, v229, v38, s[48:49]
	v_cndmask_b32_e64 v39, v229, v39, s[48:49]
	v_cndmask_b32_e64 v40, v229, v40, s[48:49]
	v_cndmask_b32_e64 v41, v229, v41, s[48:49]
	v_cndmask_b32_e64 v42, v229, v42, s[48:49]
	v_cndmask_b32_e64 v43, v229, v43, s[48:49]
	v_cndmask_b32_e64 v44, v229, v44, s[48:49]
	v_cndmask_b32_e64 v45, v229, v45, s[48:49]
	v_cndmask_b32_e64 v46, v229, v46, s[48:49]
	v_cndmask_b32_e64 v47, v229, v47, s[48:49]
	v_cndmask_b32_e64 v48, v229, v48, s[48:49]
	v_cndmask_b32_e64 v49, v229, v49, s[48:49]
	v_max3_f32 v216, v34, v35, v36
	v_max3_f32 v216, v216, v37, v38
	v_max3_f32 v216, v216, v39, v40
	v_max3_f32 v216, v216, v41, v42
	v_max3_f32 v216, v216, v43, v44
	v_max3_f32 v216, v216, v45, v46
	v_max3_f32 v216, v216, v47, v48
	v_max_f32_e32 v216, v216, v49
	v_cmp_lt_f32_e32 vcc, 4.0, v216
	s_or_b64 s[28:29], vcc, s[26:27]
	s_cmp_lg_u64 s[28:29], 0
	s_cbranch_scc0 .Lna_nr_w1s
	v_mov_b32_e32 v217, v216
	s_nop 1
	v_permlane32_swap_b32_e32 v216, v217
	v_max_f32_e32 v215, v216, v217
	s_nop 15
	v_max_f32_e32 v216, v215, v220
	v_cmp_lt_f32_e32 vcc, 0xf0c9f2ca, v215
	s_nop 1
	v_cndmask_b32_e32 v216, 0, v216, vcc
	v_exp_f32_e64 v217, -v216
	v_add_f32_e32 v212, v212, v216
	v_and_b32_e32 v217, v217, v221
	v_sub_f32_e32 v34, v34, v216
	v_sub_f32_e32 v35, v35, v216
	v_sub_f32_e32 v36, v36, v216
	v_sub_f32_e32 v37, v37, v216
	v_sub_f32_e32 v38, v38, v216
	v_sub_f32_e32 v39, v39, v216
	v_sub_f32_e32 v40, v40, v216
	v_sub_f32_e32 v41, v41, v216
	v_sub_f32_e32 v42, v42, v216
	v_sub_f32_e32 v43, v43, v216
	v_sub_f32_e32 v44, v44, v216
	v_sub_f32_e32 v45, v45, v216
	v_sub_f32_e32 v46, v46, v216
	v_sub_f32_e32 v47, v47, v216
	v_sub_f32_e32 v48, v48, v216
	v_sub_f32_e32 v49, v49, v216
	v_sub_f32_e32 v114, v114, v216
	v_sub_f32_e32 v115, v115, v216
	v_sub_f32_e32 v116, v116, v216
	v_sub_f32_e32 v117, v117, v216
	v_sub_f32_e32 v118, v118, v216
	v_sub_f32_e32 v119, v119, v216
	v_sub_f32_e32 v120, v120, v216
	v_sub_f32_e32 v121, v121, v216
	v_sub_f32_e32 v122, v122, v216
	v_sub_f32_e32 v123, v123, v216
	v_sub_f32_e32 v124, v124, v216
	v_sub_f32_e32 v125, v125, v216
	v_sub_f32_e32 v126, v126, v216
	v_sub_f32_e32 v127, v127, v216
	v_sub_f32_e32 v128, v128, v216
	v_sub_f32_e32 v129, v129, v216
	v_mul_f32_e32 v213, v213, v217
	v_mul_f32_e32 v214, v214, v217
	v_mul_f32_e32 v2, v2, v217
	v_mul_f32_e32 v3, v3, v217
	v_mul_f32_e32 v4, v4, v217
	v_mul_f32_e32 v5, v5, v217
	v_mul_f32_e32 v6, v6, v217
	v_mul_f32_e32 v7, v7, v217
	v_mul_f32_e32 v8, v8, v217
	v_mul_f32_e32 v9, v9, v217
	v_mul_f32_e32 v10, v10, v217
	v_mul_f32_e32 v11, v11, v217
	v_mul_f32_e32 v12, v12, v217
	v_mul_f32_e32 v13, v13, v217
	v_mul_f32_e32 v14, v14, v217
	v_mul_f32_e32 v15, v15, v217
	v_mul_f32_e32 v16, v16, v217
	v_mul_f32_e32 v17, v17, v217
	v_mul_f32_e32 v18, v18, v217
	v_mul_f32_e32 v19, v19, v217
	v_mul_f32_e32 v20, v20, v217
	v_mul_f32_e32 v21, v21, v217
	v_mul_f32_e32 v22, v22, v217
	v_mul_f32_e32 v23, v23, v217
	v_mul_f32_e32 v24, v24, v217
	v_mul_f32_e32 v25, v25, v217
	v_mul_f32_e32 v26, v26, v217
	v_mul_f32_e32 v27, v27, v217
	v_mul_f32_e32 v28, v28, v217
	v_mul_f32_e32 v29, v29, v217
	v_mul_f32_e32 v30, v30, v217
	v_mul_f32_e32 v31, v31, v217
	v_mul_f32_e32 v32, v32, v217
	v_mul_f32_e32 v33, v33, v217
	v_cndmask_b32_e32 v220, v220, v228, vcc
	v_cndmask_b32_e64 v221, v221, -1, vcc
	s_andn2_b64 s[26:27], s[26:27], vcc

.Lna_done_w1:
	s_add_i32 s24, s24, 1
	s_add_i32 s25, s25, 0x150
	s_sub_i32 s36, s24, s23
	s_cmp_lt_u32 s36, s63
	s_cselect_b64 s[40:41], -1, 0
	s_add_i32 s36, s36, 1
	s_cmp_lt_u32 s36, 8
	s_cselect_b64 s[44:45], -1, 0
	s_sub_i32 s37, s36, s62
	s_cmp_lt_u32 s37, 8
	s_cselect_b64 s[46:47], -1, 0
	s_and_b64 s[48:49], s[44:45], s[64:65]
	s_andn2_b64 s[38:39], s[46:47], s[64:65]
	s_or_b64 s[48:49], s[48:49], s[38:39]
	s_or_b64 s[42:43], s[44:45], s[46:47]
	s_and_b64 s[44:45], s[44:45], s[46:47]
	s_and_b64 s[44:45], s[44:45], s[40:41]
	s_cmp_eq_u64 s[44:45], 0
	s_cbranch_scc1 .Lna_slow_w0
	ds_read_b128 v[146:149], v199 offset:9216
	ds_read_b128 v[150:153], v199 offset:9248
	ds_read_b128 v[154:157], v199 offset:9280
	ds_read_b128 v[158:161], v199 offset:9312
	v_add_u32_e32 v210, s25, v208
	v_exp_f32_e32 v34, v34
	v_exp_f32_e32 v35, v35
	v_exp_f32_e32 v36, v36
	v_exp_f32_e32 v37, v37
	v_add_f32_e32 v213, v213, v34
	s_waitcnt lgkmcnt(3)
	v_mfma_f32_32x32x16_bf16 v[66:81], v[146:149], v[98:101], v[114:129]
	ds_read_b64 v[162:163], v201 offset:0
	ds_read_b64 v[164:165], v201 offset:16
	v_add_f32_e32 v214, v214, v35
	v_add_f32_e32 v213, v213, v36
	v_add_f32_e32 v214, v214, v37
	v_exp_f32_e32 v38, v38
	v_exp_f32_e32 v39, v39
	v_exp_f32_e32 v40, v40
	s_waitcnt lgkmcnt(4)
	v_mfma_f32_32x32x16_bf16 v[66:81], v[150:153], v[102:105], v[66:81]
	ds_read_b64 v[166:167], v201 offset:4352
	ds_read_b64 v[168:169], v201 offset:4368
	v_exp_f32_e32 v41, v41
	v_add_f32_e32 v213, v213, v38
	v_add_f32_e32 v214, v214, v39
	v_add_f32_e32 v213, v213, v40
	v_add_f32_e32 v214, v214, v41
	v_cvt_pk_bf16_f32 v34, v34, v35
	v_cvt_pk_bf16_f32 v35, v36, v37
	v_cvt_pk_bf16_f32 v36, v38, v39
	s_waitcnt lgkmcnt(5)
	v_mfma_f32_32x32x16_bf16 v[66:81], v[154:157], v[106:109], v[66:81]
	ds_read_b64 v[170:171], v201 offset:32
	ds_read_b64 v[172:173], v201 offset:48
	v_cvt_pk_bf16_f32 v37, v40, v41
	v_exp_f32_e32 v42, v42
	v_exp_f32_e32 v43, v43
	v_exp_f32_e32 v44, v44
	v_exp_f32_e32 v45, v45
	s_waitcnt lgkmcnt(6)
	v_mfma_f32_32x32x16_bf16 v[66:81], v[158:161], v[110:113], v[66:81]
	ds_read_b64 v[174:175], v201 offset:4384
	ds_read_b64 v[176:177], v201 offset:4400
	ds_read_b128 v[146:149], v210 offset:0
	ds_read_b128 v[150:153], v210 offset:32
	ds_read_b128 v[154:157], v210 offset:64
	ds_read_b128 v[158:161], v210 offset:96
	v_add_f32_e32 v213, v213, v42
	v_add_f32_e32 v214, v214, v43
	v_add_f32_e32 v213, v213, v44
	v_add_f32_e32 v214, v214, v45
	v_exp_f32_e32 v46, v46
	v_exp_f32_e32 v47, v47
	v_exp_f32_e32 v48, v48
	s_waitcnt lgkmcnt(10)
	v_mfma_f32_32x32x16_bf16 v[2:17], v[162:165], v[34:37], v[2:17]
	v_exp_f32_e32 v49, v49
	v_add_f32_e32 v213, v213, v46
	v_add_f32_e32 v214, v214, v47
	v_add_f32_e32 v213, v213, v48
	v_add_f32_e32 v214, v214, v49
	v_cvt_pk_bf16_f32 v42, v42, v43
	v_cvt_pk_bf16_f32 v43, v44, v45
	s_waitcnt lgkmcnt(8)
	v_mfma_f32_32x32x16_bf16 v[18:33], v[166:169], v[34:37], v[18:33]
	v_cvt_pk_bf16_f32 v44, v46, v47
	v_cvt_pk_bf16_f32 v45, v48, v49
	s_waitcnt lgkmcnt(0)
	v_add_f32_e32 v66, v66, v146
	v_add_f32_e32 v67, v67, v147
	v_add_f32_e32 v68, v68, v148
	v_add_f32_e32 v69, v69, v149
	v_add_f32_e32 v70, v70, v150
	v_add_f32_e32 v71, v71, v151
	v_add_f32_e32 v72, v72, v152
	v_mfma_f32_32x32x16_bf16 v[2:17], v[170:173], v[42:45], v[2:17]
	v_add_f32_e32 v73, v73, v153
	v_add_f32_e32 v74, v74, v154
	v_add_f32_e32 v75, v75, v155
	v_add_f32_e32 v76, v76, v156
	v_add_f32_e32 v77, v77, v157
	v_add_f32_e32 v78, v78, v158
	v_add_f32_e32 v79, v79, v159
	v_add_f32_e32 v80, v80, v160
	v_add_f32_e32 v81, v81, v161
	v_mfma_f32_32x32x16_bf16 v[18:33], v[174:177], v[42:45], v[18:33]
	s_waitcnt vmcnt(2)
	ds_write_b128 v204, v[188:191] offset:0
	ds_write_b64 v205, v[192:193] offset:8704
	ds_write_b64 v205, v[194:195] offset:8712
	global_load_dwordx4 v[188:191], v206, s[12:13]
	s_add_i32 s20, s20, 1
	s_add_u32 s12, s12, 0x2000
	s_addc_u32 s13, s13, 0
	s_cmp_eq_u32 s20, s22
	s_cselect_b32 s12, s16, s12
	s_cselect_b32 s13, s17, s13
	global_load_dwordx4 v[192:195], v207, s[14:15]
	s_add_i32 s21, s21, 1
	s_add_u32 s14, s14, 0x80
	s_addc_u32 s15, s15, 0
	s_cmp_eq_u32 s21, s22
	s_cselect_b32 s14, s18, s14
	s_cselect_b32 s15, s19, s15
	v_max3_f32 v216, v66, v67, v68
	v_max3_f32 v216, v216, v69, v70
	v_max3_f32 v216, v216, v71, v72
	v_max3_f32 v216, v216, v73, v74
	v_max3_f32 v216, v216, v75, v76
	v_max3_f32 v216, v216, v77, v78
	v_max3_f32 v216, v216, v79, v80
	v_max_f32_e32 v216, v216, v81
	v_cmp_lt_f32_e32 vcc, 4.0, v216
	s_or_b64 s[28:29], vcc, s[26:27]
	s_cmp_lg_u64 s[28:29], 0
	s_cbranch_scc0 .Lna_nr_w0f
	v_mov_b32_e32 v217, v216
	s_nop 1
	v_permlane32_swap_b32_e32 v216, v217
	v_max_f32_e32 v215, v216, v217
	s_nop 15
	v_max_f32_e32 v216, v215, v220
	v_cmp_lt_f32_e32 vcc, 0xf0c9f2ca, v215
	s_nop 1
	v_cndmask_b32_e32 v216, 0, v216, vcc
	v_exp_f32_e64 v217, -v216
	v_add_f32_e32 v212, v212, v216
	v_and_b32_e32 v217, v217, v221
	v_sub_f32_e32 v66, v66, v216
	v_sub_f32_e32 v67, v67, v216
	v_sub_f32_e32 v68, v68, v216
	v_sub_f32_e32 v69, v69, v216
	v_sub_f32_e32 v70, v70, v216
	v_sub_f32_e32 v71, v71, v216
	v_sub_f32_e32 v72, v72, v216
	v_sub_f32_e32 v73, v73, v216
	v_sub_f32_e32 v74, v74, v216
	v_sub_f32_e32 v75, v75, v216
	v_sub_f32_e32 v76, v76, v216
	v_sub_f32_e32 v77, v77, v216
	v_sub_f32_e32 v78, v78, v216
	v_sub_f32_e32 v79, v79, v216
	v_sub_f32_e32 v80, v80, v216
	v_sub_f32_e32 v81, v81, v216
	v_sub_f32_e32 v114, v114, v216
	v_sub_f32_e32 v115, v115, v216
	v_sub_f32_e32 v116, v116, v216
	v_sub_f32_e32 v117, v117, v216
	v_sub_f32_e32 v118, v118, v216
	v_sub_f32_e32 v119, v119, v216
	v_sub_f32_e32 v120, v120, v216
	v_sub_f32_e32 v121, v121, v216
	v_sub_f32_e32 v122, v122, v216
	v_sub_f32_e32 v123, v123, v216
	v_sub_f32_e32 v124, v124, v216
	v_sub_f32_e32 v125, v125, v216
	v_sub_f32_e32 v126, v126, v216
	v_sub_f32_e32 v127, v127, v216
	v_sub_f32_e32 v128, v128, v216
	v_sub_f32_e32 v129, v129, v216
	v_mul_f32_e32 v213, v213, v217
	v_mul_f32_e32 v214, v214, v217
	v_mul_f32_e32 v2, v2, v217
	v_mul_f32_e32 v3, v3, v217
	v_mul_f32_e32 v4, v4, v217
	v_mul_f32_e32 v5, v5, v217
	v_mul_f32_e32 v6, v6, v217
	v_mul_f32_e32 v7, v7, v217
	v_mul_f32_e32 v8, v8, v217
	v_mul_f32_e32 v9, v9, v217
	v_mul_f32_e32 v10, v10, v217
	v_mul_f32_e32 v11, v11, v217
	v_mul_f32_e32 v12, v12, v217
	v_mul_f32_e32 v13, v13, v217
	v_mul_f32_e32 v14, v14, v217
	v_mul_f32_e32 v15, v15, v217
	v_mul_f32_e32 v16, v16, v217
	v_mul_f32_e32 v17, v17, v217
	v_mul_f32_e32 v18, v18, v217
	v_mul_f32_e32 v19, v19, v217
	v_mul_f32_e32 v20, v20, v217
	v_mul_f32_e32 v21, v21, v217
	v_mul_f32_e32 v22, v22, v217
	v_mul_f32_e32 v23, v23, v217
	v_mul_f32_e32 v24, v24, v217
	v_mul_f32_e32 v25, v25, v217
	v_mul_f32_e32 v26, v26, v217
	v_mul_f32_e32 v27, v27, v217
	v_mul_f32_e32 v28, v28, v217
	v_mul_f32_e32 v29, v29, v217
	v_mul_f32_e32 v30, v30, v217
	v_mul_f32_e32 v31, v31, v217
	v_mul_f32_e32 v32, v32, v217
	v_mul_f32_e32 v33, v33, v217
	v_cndmask_b32_e32 v220, v220, v228, vcc
	v_cndmask_b32_e64 v221, v221, -1, vcc
	s_andn2_b64 s[26:27], s[26:27], vcc

.Lna_sl_a_w0s:
	s_waitcnt lgkmcnt(0)
	s_cmp_eq_u64 s[42:43], 0
	s_cbranch_scc1 .Lna_sl_b_w0s
	ds_read_b128 v[146:149], v199 offset:9216
	ds_read_b128 v[150:153], v199 offset:9248
	ds_read_b128 v[154:157], v199 offset:9280
	ds_read_b128 v[158:161], v199 offset:9312
	s_waitcnt lgkmcnt(3)
	v_mfma_f32_32x32x16_bf16 v[66:81], v[146:149], v[98:101], v[114:129]
	s_waitcnt lgkmcnt(2)
	v_mfma_f32_32x32x16_bf16 v[66:81], v[150:153], v[102:105], v[66:81]
	s_waitcnt lgkmcnt(1)
	v_mfma_f32_32x32x16_bf16 v[66:81], v[154:157], v[106:109], v[66:81]
	s_waitcnt lgkmcnt(0)
	v_mfma_f32_32x32x16_bf16 v[66:81], v[158:161], v[110:113], v[66:81]
	v_add_u32_e32 v210, s25, v208
	ds_read_b128 v[146:149], v210 offset:0
	ds_read_b128 v[150:153], v210 offset:32
	ds_read_b128 v[154:157], v210 offset:64
	ds_read_b128 v[158:161], v210 offset:96
	s_waitcnt lgkmcnt(0)
	s_nop 15
	v_add_f32_e32 v66, v66, v146
	v_add_f32_e32 v67, v67, v147
	v_add_f32_e32 v68, v68, v148
	v_add_f32_e32 v69, v69, v149
	v_add_f32_e32 v70, v70, v150
	v_add_f32_e32 v71, v71, v151
	v_add_f32_e32 v72, v72, v152
	v_add_f32_e32 v73, v73, v153
	v_add_f32_e32 v74, v74, v154
	v_add_f32_e32 v75, v75, v155
	v_add_f32_e32 v76, v76, v156
	v_add_f32_e32 v77, v77, v157
	v_add_f32_e32 v78, v78, v158
	v_add_f32_e32 v79, v79, v159
	v_add_f32_e32 v80, v80, v160
	v_add_f32_e32 v81, v81, v161
	v_cndmask_b32_e64 v66, v229, v66, s[48:49]
	v_cndmask_b32_e64 v67, v229, v67, s[48:49]
	v_cndmask_b32_e64 v68, v229, v68, s[48:49]
	v_cndmask_b32_e64 v69, v229, v69, s[48:49]
	v_cndmask_b32_e64 v70, v229, v70, s[48:49]
	v_cndmask_b32_e64 v71, v229, v71, s[48:49]
	v_cndmask_b32_e64 v72, v229, v72, s[48:49]
	v_cndmask_b32_e64 v73, v229, v73, s[48:49]
	v_cndmask_b32_e64 v74, v229, v74, s[48:49]
	v_cndmask_b32_e64 v75, v229, v75, s[48:49]
	v_cndmask_b32_e64 v76, v229, v76, s[48:49]
	v_cndmask_b32_e64 v77, v229, v77, s[48:49]
	v_cndmask_b32_e64 v78, v229, v78, s[48:49]
	v_cndmask_b32_e64 v79, v229, v79, s[48:49]
	v_cndmask_b32_e64 v80, v229, v80, s[48:49]
	v_cndmask_b32_e64 v81, v229, v81, s[48:49]
	v_max3_f32 v216, v66, v67, v68
	v_max3_f32 v216, v216, v69, v70
	v_max3_f32 v216, v216, v71, v72
	v_max3_f32 v216, v216, v73, v74
	v_max3_f32 v216, v216, v75, v76
	v_max3_f32 v216, v216, v77, v78
	v_max3_f32 v216, v216, v79, v80
	v_max_f32_e32 v216, v216, v81
	v_cmp_lt_f32_e32 vcc, 4.0, v216
	s_or_b64 s[28:29], vcc, s[26:27]
	s_cmp_lg_u64 s[28:29], 0
	s_cbranch_scc0 .Lna_nr_w0s
	v_mov_b32_e32 v217, v216
	s_nop 1
	v_permlane32_swap_b32_e32 v216, v217
	v_max_f32_e32 v215, v216, v217
	s_nop 15
	v_max_f32_e32 v216, v215, v220
	v_cmp_lt_f32_e32 vcc, 0xf0c9f2ca, v215
	s_nop 1
	v_cndmask_b32_e32 v216, 0, v216, vcc
	v_exp_f32_e64 v217, -v216
	v_add_f32_e32 v212, v212, v216
	v_and_b32_e32 v217, v217, v221
	v_sub_f32_e32 v66, v66, v216
	v_sub_f32_e32 v67, v67, v216
	v_sub_f32_e32 v68, v68, v216
	v_sub_f32_e32 v69, v69, v216
	v_sub_f32_e32 v70, v70, v216
	v_sub_f32_e32 v71, v71, v216
	v_sub_f32_e32 v72, v72, v216
	v_sub_f32_e32 v73, v73, v216
	v_sub_f32_e32 v74, v74, v216
	v_sub_f32_e32 v75, v75, v216
	v_sub_f32_e32 v76, v76, v216
	v_sub_f32_e32 v77, v77, v216
	v_sub_f32_e32 v78, v78, v216
	v_sub_f32_e32 v79, v79, v216
	v_sub_f32_e32 v80, v80, v216
	v_sub_f32_e32 v81, v81, v216
	v_sub_f32_e32 v114, v114, v216
	v_sub_f32_e32 v115, v115, v216
	v_sub_f32_e32 v116, v116, v216
	v_sub_f32_e32 v117, v117, v216
	v_sub_f32_e32 v118, v118, v216
	v_sub_f32_e32 v119, v119, v216
	v_sub_f32_e32 v120, v120, v216
	v_sub_f32_e32 v121, v121, v216
	v_sub_f32_e32 v122, v122, v216
	v_sub_f32_e32 v123, v123, v216
	v_sub_f32_e32 v124, v124, v216
	v_sub_f32_e32 v125, v125, v216
	v_sub_f32_e32 v126, v126, v216
	v_sub_f32_e32 v127, v127, v216
	v_sub_f32_e32 v128, v128, v216
	v_sub_f32_e32 v129, v129, v216
	v_mul_f32_e32 v213, v213, v217
	v_mul_f32_e32 v214, v214, v217
	v_mul_f32_e32 v2, v2, v217
	v_mul_f32_e32 v3, v3, v217
	v_mul_f32_e32 v4, v4, v217
	v_mul_f32_e32 v5, v5, v217
	v_mul_f32_e32 v6, v6, v217
	v_mul_f32_e32 v7, v7, v217
	v_mul_f32_e32 v8, v8, v217
	v_mul_f32_e32 v9, v9, v217
	v_mul_f32_e32 v10, v10, v217
	v_mul_f32_e32 v11, v11, v217
	v_mul_f32_e32 v12, v12, v217
	v_mul_f32_e32 v13, v13, v217
	v_mul_f32_e32 v14, v14, v217
	v_mul_f32_e32 v15, v15, v217
	v_mul_f32_e32 v16, v16, v217
	v_mul_f32_e32 v17, v17, v217
	v_mul_f32_e32 v18, v18, v217
	v_mul_f32_e32 v19, v19, v217
	v_mul_f32_e32 v20, v20, v217
	v_mul_f32_e32 v21, v21, v217
	v_mul_f32_e32 v22, v22, v217
	v_mul_f32_e32 v23, v23, v217
	v_mul_f32_e32 v24, v24, v217
	v_mul_f32_e32 v25, v25, v217
	v_mul_f32_e32 v26, v26, v217
	v_mul_f32_e32 v27, v27, v217
	v_mul_f32_e32 v28, v28, v217
	v_mul_f32_e32 v29, v29, v217
	v_mul_f32_e32 v30, v30, v217
	v_mul_f32_e32 v31, v31, v217
	v_mul_f32_e32 v32, v32, v217
	v_mul_f32_e32 v33, v33, v217
	v_cndmask_b32_e32 v220, v220, v228, vcc
	v_cndmask_b32_e64 v221, v221, -1, vcc
	s_andn2_b64 s[26:27], s[26:27], vcc

.Lna_done_w0:
	s_add_i32 s24, s24, 1
	s_add_i32 s25, s25, 0x150
	s_add_i32 s33, s33, -1
	s_cmp_lg_u32 s33, 0
	s_cbranch_scc1 .Lna_wloop
	v_sub_f32_e32 v114, 0, v212
	v_mov_b32_e32 v115, v114
	v_mov_b32_e32 v116, v114
	v_mov_b32_e32 v117, v114
	v_mov_b32_e32 v118, v114
	v_mov_b32_e32 v119, v114
	v_mov_b32_e32 v120, v114
	v_mov_b32_e32 v121, v114
	v_mov_b32_e32 v122, v114
	v_mov_b32_e32 v123, v114
	v_mov_b32_e32 v124, v114
	v_mov_b32_e32 v125, v114
	v_mov_b32_e32 v126, v114
	v_mov_b32_e32 v127, v114
	v_mov_b32_e32 v128, v114
	v_mov_b32_e32 v129, v114
	v_mov_b32_e32 v130, v114
	v_mov_b32_e32 v131, v114
	v_mov_b32_e32 v132, v114
	v_mov_b32_e32 v133, v114
	v_mov_b32_e32 v134, v114
	v_mov_b32_e32 v135, v114
	v_mov_b32_e32 v136, v114
	v_mov_b32_e32 v137, v114
	v_mov_b32_e32 v138, v114
	v_mov_b32_e32 v139, v114
	v_mov_b32_e32 v140, v114
	v_mov_b32_e32 v141, v114
	v_mov_b32_e32 v142, v114
	v_mov_b32_e32 v143, v114
	v_mov_b32_e32 v144, v114
	v_mov_b32_e32 v145, v114
	s_sub_i32 s36, s24, s23
	s_cmp_lt_u32 s36, s63
	s_cselect_b64 s[40:41], -1, 0
	s_mov_b64 s[42:43], -1
	s_cmp_eq_u64 s[40:41], 0
	s_cbranch_scc1 .Lna_slow_wc
	ds_read_b128 v[146:149], v200 offset:0
	ds_read_b128 v[150:153], v200 offset:4608
	ds_read_b128 v[154:157], v200 offset:32
	ds_read_b128 v[158:161], v200 offset:4640
	v_exp_f32_e32 v66, v66
	v_exp_f32_e32 v67, v67
	v_exp_f32_e32 v68, v68
	s_waitcnt lgkmcnt(2)
	v_mfma_f32_32x32x16_bf16 v[34:49], v[146:149], v[98:101], v[114:129]
	ds_read_b128 v[146:149], v200 offset:64
	v_exp_f32_e32 v69, v69
	v_add_f32_e32 v213, v213, v66
	v_add_f32_e32 v214, v214, v67
	v_add_f32_e32 v213, v213, v68
	v_add_f32_e32 v214, v214, v69
	v_mfma_f32_32x32x16_bf16 v[50:65], v[150:153], v[98:101], v[130:145]
	ds_read_b128 v[150:153], v200 offset:4672
	v_exp_f32_e32 v70, v70
	v_exp_f32_e32 v71, v71
	v_exp_f32_e32 v72, v72
	s_waitcnt lgkmcnt(2)
	v_mfma_f32_32x32x16_bf16 v[34:49], v[154:157], v[102:105], v[34:49]
	ds_read_b128 v[154:157], v200 offset:96
	v_exp_f32_e32 v73, v73
	v_add_f32_e32 v213, v213, v70
	v_add_f32_e32 v214, v214, v71
	v_add_f32_e32 v213, v213, v72
	v_mfma_f32_32x32x16_bf16 v[50:65], v[158:161], v[102:105], v[50:65]
	ds_read_b128 v[158:161], v200 offset:4704
	v_add_f32_e32 v214, v214, v73
	v_cvt_pk_bf16_f32 v66, v66, v67
	v_cvt_pk_bf16_f32 v67, v68, v69
	v_cvt_pk_bf16_f32 v68, v70, v71
	v_cvt_pk_bf16_f32 v69, v72, v73
	v_exp_f32_e32 v74, v74
	s_waitcnt lgkmcnt(2)
	v_mfma_f32_32x32x16_bf16 v[34:49], v[146:149], v[106:109], v[34:49]
	ds_read_b64 v[162:163], v201 offset:8704
	ds_read_b64 v[164:165], v201 offset:8720
	v_exp_f32_e32 v75, v75
	v_exp_f32_e32 v76, v76
	v_mfma_f32_32x32x16_bf16 v[50:65], v[150:153], v[106:109], v[50:65]
	ds_read_b64 v[166:167], v201 offset:13056
	ds_read_b64 v[168:169], v201 offset:13072
	v_exp_f32_e32 v77, v77
	v_add_f32_e32 v213, v213, v74
	v_add_f32_e32 v214, v214, v75
	v_add_f32_e32 v213, v213, v76
	v_add_f32_e32 v214, v214, v77
	s_waitcnt lgkmcnt(4)
	v_mfma_f32_32x32x16_bf16 v[34:49], v[154:157], v[110:113], v[34:49]
	ds_read_b64 v[170:171], v201 offset:8736
	ds_read_b64 v[172:173], v201 offset:8752
	v_exp_f32_e32 v78, v78
	v_exp_f32_e32 v79, v79
	v_exp_f32_e32 v80, v80
	v_mfma_f32_32x32x16_bf16 v[50:65], v[158:161], v[110:113], v[50:65]
	ds_read_b64 v[174:175], v201 offset:13088
	ds_read_b64 v[176:177], v201 offset:13104
	v_exp_f32_e32 v81, v81
	v_add_f32_e32 v213, v213, v78
	v_add_f32_e32 v214, v214, v79
	v_add_f32_e32 v213, v213, v80
	s_waitcnt lgkmcnt(6)
	v_mfma_f32_32x32x16_bf16 v[2:17], v[162:165], v[66:69], v[2:17]
	v_add_f32_e32 v214, v214, v81
	v_cvt_pk_bf16_f32 v74, v74, v75
	v_cvt_pk_bf16_f32 v75, v76, v77
	v_cvt_pk_bf16_f32 v76, v78, v79
	v_cvt_pk_bf16_f32 v77, v80, v81
	s_waitcnt lgkmcnt(4)
	v_mfma_f32_32x32x16_bf16 v[18:33], v[166:169], v[66:69], v[18:33]
	v_max3_f32 v216, v34, v35, v36
	v_max3_f32 v216, v216, v37, v38
	v_max3_f32 v216, v216, v39, v40
	v_max3_f32 v216, v216, v41, v42
	v_max3_f32 v216, v216, v43, v44
	v_max3_f32 v216, v216, v45, v46
	s_waitcnt lgkmcnt(2)
	v_mfma_f32_32x32x16_bf16 v[2:17], v[170:173], v[74:77], v[2:17]
	v_max3_f32 v216, v216, v47, v48
	v_max3_f32 v216, v216, v49, v50
	v_max3_f32 v216, v216, v51, v52
	v_max3_f32 v216, v216, v53, v54
	v_max3_f32 v216, v216, v55, v56
	v_max3_f32 v216, v216, v57, v58
	s_waitcnt lgkmcnt(0)
	v_mfma_f32_32x32x16_bf16 v[18:33], v[174:177], v[74:77], v[18:33]
	s_waitcnt vmcnt(2)
	ds_write_b128 v204, v[230:233] offset:9216
	ds_write_b64 v205, v[234:235] offset:0
	ds_write_b64 v205, v[236:237] offset:8
	global_load_dwordx4 v[230:233], v206, s[12:13]
	s_add_u32 s12, s12, 0x2000
	s_addc_u32 s13, s13, 0
	global_load_dwordx4 v[234:237], v207, s[14:15]
	s_add_u32 s14, s14, 0x80
	s_addc_u32 s15, s15, 0
	v_max3_f32 v216, v216, v59, v60
	v_max3_f32 v216, v216, v61, v62
	v_max3_f32 v216, v216, v63, v64
	v_max_f32_e32 v216, v216, v65
	v_cmp_lt_f32_e32 vcc, 4.0, v216
	s_cbranch_vccz .Lna_nr_wcf
	v_mov_b32_e32 v217, v216
	s_nop 1
	v_permlane32_swap_b32_e32 v216, v217
	v_max_f32_e32 v215, v216, v217
	s_nop 15
	v_max_f32_e32 v216, v215, v220
	v_exp_f32_e64 v217, -v216
	v_add_f32_e32 v212, v212, v216
	v_and_b32_e32 v217, v217, v221
	v_sub_f32_e32 v34, v34, v216
	v_sub_f32_e32 v35, v35, v216
	v_sub_f32_e32 v36, v36, v216
	v_sub_f32_e32 v37, v37, v216
	v_sub_f32_e32 v38, v38, v216
	v_sub_f32_e32 v39, v39, v216
	v_sub_f32_e32 v40, v40, v216
	v_sub_f32_e32 v41, v41, v216
	v_sub_f32_e32 v42, v42, v216
	v_sub_f32_e32 v43, v43, v216
	v_sub_f32_e32 v44, v44, v216
	v_sub_f32_e32 v45, v45, v216
	v_sub_f32_e32 v46, v46, v216
	v_sub_f32_e32 v47, v47, v216
	v_sub_f32_e32 v48, v48, v216
	v_sub_f32_e32 v49, v49, v216
	v_sub_f32_e32 v50, v50, v216
	v_sub_f32_e32 v51, v51, v216
	v_sub_f32_e32 v52, v52, v216
	v_sub_f32_e32 v53, v53, v216
	v_sub_f32_e32 v54, v54, v216
	v_sub_f32_e32 v55, v55, v216
	v_sub_f32_e32 v56, v56, v216
	v_sub_f32_e32 v57, v57, v216
	v_sub_f32_e32 v58, v58, v216
	v_sub_f32_e32 v59, v59, v216
	v_sub_f32_e32 v60, v60, v216
	v_sub_f32_e32 v61, v61, v216
	v_sub_f32_e32 v62, v62, v216
	v_sub_f32_e32 v63, v63, v216
	v_sub_f32_e32 v64, v64, v216
	v_sub_f32_e32 v65, v65, v216
	v_sub_f32_e32 v114, v114, v216
	v_sub_f32_e32 v115, v115, v216
	v_sub_f32_e32 v116, v116, v216
	v_sub_f32_e32 v117, v117, v216
	v_sub_f32_e32 v118, v118, v216
	v_sub_f32_e32 v119, v119, v216
	v_sub_f32_e32 v120, v120, v216
	v_sub_f32_e32 v121, v121, v216
	v_sub_f32_e32 v122, v122, v216
	v_sub_f32_e32 v123, v123, v216
	v_sub_f32_e32 v124, v124, v216
	v_sub_f32_e32 v125, v125, v216
	v_sub_f32_e32 v126, v126, v216
	v_sub_f32_e32 v127, v127, v216
	v_sub_f32_e32 v128, v128, v216
	v_sub_f32_e32 v129, v129, v216
	v_sub_f32_e32 v130, v130, v216
	v_sub_f32_e32 v131, v131, v216
	v_sub_f32_e32 v132, v132, v216
	v_sub_f32_e32 v133, v133, v216
	v_sub_f32_e32 v134, v134, v216
	v_sub_f32_e32 v135, v135, v216
	v_sub_f32_e32 v136, v136, v216
	v_sub_f32_e32 v137, v137, v216
	v_sub_f32_e32 v138, v138, v216
	v_sub_f32_e32 v139, v139, v216
	v_sub_f32_e32 v140, v140, v216
	v_sub_f32_e32 v141, v141, v216
	v_sub_f32_e32 v142, v142, v216
	v_sub_f32_e32 v143, v143, v216
	v_sub_f32_e32 v144, v144, v216
	v_sub_f32_e32 v145, v145, v216
	v_mul_f32_e32 v213, v213, v217
	v_mul_f32_e32 v214, v214, v217
	v_mul_f32_e32 v2, v2, v217
	v_mul_f32_e32 v3, v3, v217
	v_mul_f32_e32 v4, v4, v217
	v_mul_f32_e32 v5, v5, v217
	v_mul_f32_e32 v6, v6, v217
	v_mul_f32_e32 v7, v7, v217
	v_mul_f32_e32 v8, v8, v217
	v_mul_f32_e32 v9, v9, v217
	v_mul_f32_e32 v10, v10, v217
	v_mul_f32_e32 v11, v11, v217
	v_mul_f32_e32 v12, v12, v217
	v_mul_f32_e32 v13, v13, v217
	v_mul_f32_e32 v14, v14, v217
	v_mul_f32_e32 v15, v15, v217
	v_mul_f32_e32 v16, v16, v217
	v_mul_f32_e32 v17, v17, v217
	v_mul_f32_e32 v18, v18, v217
	v_mul_f32_e32 v19, v19, v217
	v_mul_f32_e32 v20, v20, v217
	v_mul_f32_e32 v21, v21, v217
	v_mul_f32_e32 v22, v22, v217
	v_mul_f32_e32 v23, v23, v217
	v_mul_f32_e32 v24, v24, v217
	v_mul_f32_e32 v25, v25, v217
	v_mul_f32_e32 v26, v26, v217
	v_mul_f32_e32 v27, v27, v217
	v_mul_f32_e32 v28, v28, v217
	v_mul_f32_e32 v29, v29, v217
	v_mul_f32_e32 v30, v30, v217
	v_mul_f32_e32 v31, v31, v217
	v_mul_f32_e32 v32, v32, v217
	v_mul_f32_e32 v33, v33, v217

.Lna_sl_a_wcs:
	s_waitcnt lgkmcnt(0)
	s_cmp_eq_u64 s[42:43], 0
	s_cbranch_scc1 .Lna_sl_b_wcs
	ds_read_b128 v[146:149], v200 offset:0
	ds_read_b128 v[150:153], v200 offset:4608
	ds_read_b128 v[154:157], v200 offset:32
	ds_read_b128 v[158:161], v200 offset:4640
	ds_read_b128 v[162:165], v200 offset:64
	ds_read_b128 v[166:169], v200 offset:4672
	ds_read_b128 v[170:173], v200 offset:96
	ds_read_b128 v[174:177], v200 offset:4704
	s_waitcnt lgkmcnt(7)
	v_mfma_f32_32x32x16_bf16 v[34:49], v[146:149], v[98:101], v[114:129]
	s_waitcnt lgkmcnt(6)
	v_mfma_f32_32x32x16_bf16 v[50:65], v[150:153], v[98:101], v[130:145]
	s_waitcnt lgkmcnt(5)
	v_mfma_f32_32x32x16_bf16 v[34:49], v[154:157], v[102:105], v[34:49]
	s_waitcnt lgkmcnt(4)
	v_mfma_f32_32x32x16_bf16 v[50:65], v[158:161], v[102:105], v[50:65]
	s_waitcnt lgkmcnt(3)
	v_mfma_f32_32x32x16_bf16 v[34:49], v[162:165], v[106:109], v[34:49]
	s_waitcnt lgkmcnt(2)
	v_mfma_f32_32x32x16_bf16 v[50:65], v[166:169], v[106:109], v[50:65]
	s_waitcnt lgkmcnt(1)
	v_mfma_f32_32x32x16_bf16 v[34:49], v[170:173], v[110:113], v[34:49]
	s_waitcnt lgkmcnt(0)
	v_mfma_f32_32x32x16_bf16 v[50:65], v[174:177], v[110:113], v[50:65]
	s_nop 15
	v_max3_f32 v216, v34, v35, v36
	v_max3_f32 v216, v216, v37, v38
	v_max3_f32 v216, v216, v39, v40
	v_max3_f32 v216, v216, v41, v42
	v_max3_f32 v216, v216, v43, v44
	v_max3_f32 v216, v216, v45, v46
	v_max3_f32 v216, v216, v47, v48
	v_max3_f32 v216, v216, v49, v50
	v_max3_f32 v216, v216, v51, v52
	v_max3_f32 v216, v216, v53, v54
	v_max3_f32 v216, v216, v55, v56
	v_max3_f32 v216, v216, v57, v58
	v_max3_f32 v216, v216, v59, v60
	v_max3_f32 v216, v216, v61, v62
	v_max3_f32 v216, v216, v63, v64
	v_max_f32_e32 v216, v216, v65
	v_cmp_lt_f32_e32 vcc, 4.0, v216
	s_cbranch_vccz .Lna_nr_wcs
	v_mov_b32_e32 v217, v216
	s_nop 1
	v_permlane32_swap_b32_e32 v216, v217
	v_max_f32_e32 v215, v216, v217
	s_nop 15
	v_max_f32_e32 v216, v215, v220
	v_exp_f32_e64 v217, -v216
	v_add_f32_e32 v212, v212, v216
	v_and_b32_e32 v217, v217, v221
	v_sub_f32_e32 v34, v34, v216
	v_sub_f32_e32 v35, v35, v216
	v_sub_f32_e32 v36, v36, v216
	v_sub_f32_e32 v37, v37, v216
	v_sub_f32_e32 v38, v38, v216
	v_sub_f32_e32 v39, v39, v216
	v_sub_f32_e32 v40, v40, v216
	v_sub_f32_e32 v41, v41, v216
	v_sub_f32_e32 v42, v42, v216
	v_sub_f32_e32 v43, v43, v216
	v_sub_f32_e32 v44, v44, v216
	v_sub_f32_e32 v45, v45, v216
	v_sub_f32_e32 v46, v46, v216
	v_sub_f32_e32 v47, v47, v216
	v_sub_f32_e32 v48, v48, v216
	v_sub_f32_e32 v49, v49, v216
	v_sub_f32_e32 v50, v50, v216
	v_sub_f32_e32 v51, v51, v216
	v_sub_f32_e32 v52, v52, v216
	v_sub_f32_e32 v53, v53, v216
	v_sub_f32_e32 v54, v54, v216
	v_sub_f32_e32 v55, v55, v216
	v_sub_f32_e32 v56, v56, v216
	v_sub_f32_e32 v57, v57, v216
	v_sub_f32_e32 v58, v58, v216
	v_sub_f32_e32 v59, v59, v216
	v_sub_f32_e32 v60, v60, v216
	v_sub_f32_e32 v61, v61, v216
	v_sub_f32_e32 v62, v62, v216
	v_sub_f32_e32 v63, v63, v216
	v_sub_f32_e32 v64, v64, v216
	v_sub_f32_e32 v65, v65, v216
	v_sub_f32_e32 v114, v114, v216
	v_sub_f32_e32 v115, v115, v216
	v_sub_f32_e32 v116, v116, v216
	v_sub_f32_e32 v117, v117, v216
	v_sub_f32_e32 v118, v118, v216
	v_sub_f32_e32 v119, v119, v216
	v_sub_f32_e32 v120, v120, v216
	v_sub_f32_e32 v121, v121, v216
	v_sub_f32_e32 v122, v122, v216
	v_sub_f32_e32 v123, v123, v216
	v_sub_f32_e32 v124, v124, v216
	v_sub_f32_e32 v125, v125, v216
	v_sub_f32_e32 v126, v126, v216
	v_sub_f32_e32 v127, v127, v216
	v_sub_f32_e32 v128, v128, v216
	v_sub_f32_e32 v129, v129, v216
	v_sub_f32_e32 v130, v130, v216
	v_sub_f32_e32 v131, v131, v216
	v_sub_f32_e32 v132, v132, v216
	v_sub_f32_e32 v133, v133, v216
	v_sub_f32_e32 v134, v134, v216
	v_sub_f32_e32 v135, v135, v216
	v_sub_f32_e32 v136, v136, v216
	v_sub_f32_e32 v137, v137, v216
	v_sub_f32_e32 v138, v138, v216
	v_sub_f32_e32 v139, v139, v216
	v_sub_f32_e32 v140, v140, v216
	v_sub_f32_e32 v141, v141, v216
	v_sub_f32_e32 v142, v142, v216
	v_sub_f32_e32 v143, v143, v216
	v_sub_f32_e32 v144, v144, v216
	v_sub_f32_e32 v145, v145, v216
	v_mul_f32_e32 v213, v213, v217
	v_mul_f32_e32 v214, v214, v217
	v_mul_f32_e32 v2, v2, v217
	v_mul_f32_e32 v3, v3, v217
	v_mul_f32_e32 v4, v4, v217
	v_mul_f32_e32 v5, v5, v217
	v_mul_f32_e32 v6, v6, v217
	v_mul_f32_e32 v7, v7, v217
	v_mul_f32_e32 v8, v8, v217
	v_mul_f32_e32 v9, v9, v217
	v_mul_f32_e32 v10, v10, v217
	v_mul_f32_e32 v11, v11, v217
	v_mul_f32_e32 v12, v12, v217
	v_mul_f32_e32 v13, v13, v217
	v_mul_f32_e32 v14, v14, v217
	v_mul_f32_e32 v15, v15, v217
	v_mul_f32_e32 v16, v16, v217
	v_mul_f32_e32 v17, v17, v217
	v_mul_f32_e32 v18, v18, v217
	v_mul_f32_e32 v19, v19, v217
	v_mul_f32_e32 v20, v20, v217
	v_mul_f32_e32 v21, v21, v217
	v_mul_f32_e32 v22, v22, v217
	v_mul_f32_e32 v23, v23, v217
	v_mul_f32_e32 v24, v24, v217
	v_mul_f32_e32 v25, v25, v217
	v_mul_f32_e32 v26, v26, v217
	v_mul_f32_e32 v27, v27, v217
	v_mul_f32_e32 v28, v28, v217
	v_mul_f32_e32 v29, v29, v217
	v_mul_f32_e32 v30, v30, v217
	v_mul_f32_e32 v31, v31, v217
	v_mul_f32_e32 v32, v32, v217
	v_mul_f32_e32 v33, v33, v217

.Lna_done_wc:
	ds_read_b128 v[146:149], v200 offset:9216
	ds_read_b128 v[150:153], v200 offset:13824
	ds_read_b128 v[154:157], v200 offset:9248
	ds_read_b128 v[158:161], v200 offset:13856
	v_exp_f32_e32 v34, v34
	v_exp_f32_e32 v35, v35
	v_exp_f32_e32 v36, v36
	v_exp_f32_e32 v37, v37
	s_waitcnt lgkmcnt(2)
	v_mfma_f32_32x32x16_bf16 v[66:81], v[146:149], v[98:101], v[114:129]
	ds_read_b128 v[146:149], v200 offset:9280
	v_add_f32_e32 v213, v213, v34
	v_add_f32_e32 v214, v214, v35
	v_add_f32_e32 v213, v213, v36
	v_add_f32_e32 v214, v214, v37
	v_exp_f32_e32 v38, v38
	v_exp_f32_e32 v39, v39
	v_mfma_f32_32x32x16_bf16 v[82:97], v[150:153], v[98:101], v[130:145]
	ds_read_b128 v[150:153], v200 offset:13888
	v_exp_f32_e32 v40, v40
	v_exp_f32_e32 v41, v41
	v_add_f32_e32 v213, v213, v38
	v_add_f32_e32 v214, v214, v39
	v_add_f32_e32 v213, v213, v40
	s_waitcnt lgkmcnt(2)
	v_mfma_f32_32x32x16_bf16 v[66:81], v[154:157], v[102:105], v[66:81]
	ds_read_b128 v[154:157], v200 offset:9312
	v_add_f32_e32 v214, v214, v41
	v_cvt_pk_bf16_f32 v34, v34, v35
	v_cvt_pk_bf16_f32 v35, v36, v37
	v_cvt_pk_bf16_f32 v36, v38, v39
	v_cvt_pk_bf16_f32 v37, v40, v41
	v_exp_f32_e32 v42, v42
	v_exp_f32_e32 v43, v43
	v_mfma_f32_32x32x16_bf16 v[82:97], v[158:161], v[102:105], v[82:97]
	ds_read_b128 v[158:161], v200 offset:13920
	v_exp_f32_e32 v44, v44
	v_exp_f32_e32 v45, v45
	v_add_f32_e32 v213, v213, v42
	v_add_f32_e32 v214, v214, v43
	s_waitcnt lgkmcnt(2)
	v_mfma_f32_32x32x16_bf16 v[66:81], v[146:149], v[106:109], v[66:81]
	ds_read_b64 v[162:163], v202 offset:0
	ds_read_b64 v[164:165], v202 offset:16
	v_add_f32_e32 v213, v213, v44
	v_add_f32_e32 v214, v214, v45
	v_exp_f32_e32 v46, v46
	v_exp_f32_e32 v47, v47
	v_exp_f32_e32 v48, v48
	v_mfma_f32_32x32x16_bf16 v[82:97], v[150:153], v[106:109], v[82:97]
	ds_read_b64 v[166:167], v202 offset:4352
	ds_read_b64 v[168:169], v202 offset:4368
	v_exp_f32_e32 v49, v49
	v_add_f32_e32 v213, v213, v46
	v_add_f32_e32 v214, v214, v47
	v_add_f32_e32 v213, v213, v48
	v_add_f32_e32 v214, v214, v49
	v_cvt_pk_bf16_f32 v42, v42, v43
	v_cvt_pk_bf16_f32 v43, v44, v45
	s_waitcnt lgkmcnt(4)
	v_mfma_f32_32x32x16_bf16 v[66:81], v[154:157], v[110:113], v[66:81]
	ds_read_b64 v[170:171], v202 offset:32
	ds_read_b64 v[172:173], v202 offset:48
	v_cvt_pk_bf16_f32 v44, v46, v47
	v_cvt_pk_bf16_f32 v45, v48, v49
	v_exp_f32_e32 v50, v50
	v_exp_f32_e32 v51, v51
	v_exp_f32_e32 v52, v52
	v_mfma_f32_32x32x16_bf16 v[82:97], v[158:161], v[110:113], v[82:97]
	ds_read_b64 v[174:175], v202 offset:4384
	ds_read_b64 v[176:177], v202 offset:4400
	v_exp_f32_e32 v53, v53
	v_add_f32_e32 v213, v213, v50
	v_add_f32_e32 v214, v214, v51
	v_add_f32_e32 v213, v213, v52
	v_add_f32_e32 v214, v214, v53
	v_exp_f32_e32 v54, v54
	s_waitcnt lgkmcnt(6)
	v_mfma_f32_32x32x16_bf16 v[2:17], v[162:165], v[34:37], v[2:17]
	ds_read_b64 v[162:163], v202 offset:64
	ds_read_b64 v[164:165], v202 offset:80
	v_exp_f32_e32 v55, v55
	v_exp_f32_e32 v56, v56
	v_exp_f32_e32 v57, v57
	s_waitcnt lgkmcnt(6)
	v_mfma_f32_32x32x16_bf16 v[18:33], v[166:169], v[34:37], v[18:33]
	ds_read_b64 v[166:167], v202 offset:4416
	ds_read_b64 v[168:169], v202 offset:4432
	v_add_f32_e32 v213, v213, v54
	v_add_f32_e32 v214, v214, v55
	v_add_f32_e32 v213, v213, v56
	v_add_f32_e32 v214, v214, v57
	v_cvt_pk_bf16_f32 v50, v50, v51
	v_cvt_pk_bf16_f32 v51, v52, v53
	v_cvt_pk_bf16_f32 v52, v54, v55
	v_cvt_pk_bf16_f32 v53, v56, v57
	s_waitcnt lgkmcnt(6)
	v_mfma_f32_32x32x16_bf16 v[2:17], v[170:173], v[42:45], v[2:17]
	ds_read_b64 v[170:171], v202 offset:96
	ds_read_b64 v[172:173], v202 offset:112
	v_exp_f32_e32 v58, v58
	v_exp_f32_e32 v59, v59
	v_exp_f32_e32 v60, v60
	v_exp_f32_e32 v61, v61
	s_waitcnt lgkmcnt(6)
	v_mfma_f32_32x32x16_bf16 v[18:33], v[174:177], v[42:45], v[18:33]
	ds_read_b64 v[174:175], v202 offset:4448
	ds_read_b64 v[176:177], v202 offset:4464
	s_waitcnt vmcnt(2)
	ds_write_b128 v204, v[188:191] offset:0
	ds_write_b64 v205, v[192:193] offset:8704
	ds_write_b64 v205, v[194:195] offset:8712
	global_load_dwordx4 v[192:195], v207, s[14:15]
	s_add_u32 s14, s14, 0x80
	s_addc_u32 s15, s15, 0
	v_add_f32_e32 v213, v213, v58
	v_add_f32_e32 v214, v214, v59
	v_add_f32_e32 v213, v213, v60
	v_add_f32_e32 v214, v214, v61
	v_exp_f32_e32 v62, v62
	v_exp_f32_e32 v63, v63
	s_waitcnt lgkmcnt(9)
	v_mfma_f32_32x32x16_bf16 v[2:17], v[162:165], v[50:53], v[2:17]
	v_exp_f32_e32 v64, v64
	v_exp_f32_e32 v65, v65
	v_add_f32_e32 v213, v213, v62
	v_add_f32_e32 v214, v214, v63
	v_add_f32_e32 v213, v213, v64
	s_waitcnt lgkmcnt(7)
	v_mfma_f32_32x32x16_bf16 v[18:33], v[166:169], v[50:53], v[18:33]
	v_add_f32_e32 v214, v214, v65
	v_cvt_pk_bf16_f32 v58, v58, v59
	v_cvt_pk_bf16_f32 v59, v60, v61
	v_cvt_pk_bf16_f32 v60, v62, v63
	v_cvt_pk_bf16_f32 v61, v64, v65
	v_max3_f32 v216, v66, v67, v68
	v_max3_f32 v216, v216, v69, v70
	s_waitcnt lgkmcnt(5)
	v_mfma_f32_32x32x16_bf16 v[2:17], v[170:173], v[58:61], v[2:17]
	v_max3_f32 v216, v216, v71, v72
	v_max3_f32 v216, v216, v73, v74
	v_max3_f32 v216, v216, v75, v76
	v_max3_f32 v216, v216, v77, v78
	v_max3_f32 v216, v216, v79, v80
	v_max3_f32 v216, v216, v81, v82
	v_max3_f32 v216, v216, v83, v84
	v_max3_f32 v216, v216, v85, v86
	s_waitcnt lgkmcnt(3)
	v_mfma_f32_32x32x16_bf16 v[18:33], v[174:177], v[58:61], v[18:33]
	v_max3_f32 v216, v216, v87, v88
	v_max3_f32 v216, v216, v89, v90
	v_max3_f32 v216, v216, v91, v92
	v_max3_f32 v216, v216, v93, v94
	v_max3_f32 v216, v216, v95, v96
	v_max_f32_e32 v216, v216, v97
	v_cmp_lt_f32_e32 vcc, 4.0, v216
	s_cbranch_vccz .Lna_nr_c0
	v_mov_b32_e32 v217, v216
	s_nop 1
	v_permlane32_swap_b32_e32 v216, v217
	v_max_f32_e32 v215, v216, v217
	s_nop 15
	v_max_f32_e32 v216, v215, v220
	v_exp_f32_e64 v217, -v216
	v_add_f32_e32 v212, v212, v216
	v_and_b32_e32 v217, v217, v221
	v_sub_f32_e32 v66, v66, v216
	v_sub_f32_e32 v67, v67, v216
	v_sub_f32_e32 v68, v68, v216
	v_sub_f32_e32 v69, v69, v216
	v_sub_f32_e32 v70, v70, v216
	v_sub_f32_e32 v71, v71, v216
	v_sub_f32_e32 v72, v72, v216
	v_sub_f32_e32 v73, v73, v216
	v_sub_f32_e32 v74, v74, v216
	v_sub_f32_e32 v75, v75, v216
	v_sub_f32_e32 v76, v76, v216
	v_sub_f32_e32 v77, v77, v216
	v_sub_f32_e32 v78, v78, v216
	v_sub_f32_e32 v79, v79, v216
	v_sub_f32_e32 v80, v80, v216
	v_sub_f32_e32 v81, v81, v216
	v_sub_f32_e32 v82, v82, v216
	v_sub_f32_e32 v83, v83, v216
	v_sub_f32_e32 v84, v84, v216
	v_sub_f32_e32 v85, v85, v216
	v_sub_f32_e32 v86, v86, v216
	v_sub_f32_e32 v87, v87, v216
	v_sub_f32_e32 v88, v88, v216
	v_sub_f32_e32 v89, v89, v216
	v_sub_f32_e32 v90, v90, v216
	v_sub_f32_e32 v91, v91, v216
	v_sub_f32_e32 v92, v92, v216
	v_sub_f32_e32 v93, v93, v216
	v_sub_f32_e32 v94, v94, v216
	v_sub_f32_e32 v95, v95, v216
	v_sub_f32_e32 v96, v96, v216
	v_sub_f32_e32 v97, v97, v216
	v_sub_f32_e32 v114, v114, v216
	v_sub_f32_e32 v115, v115, v216
	v_sub_f32_e32 v116, v116, v216
	v_sub_f32_e32 v117, v117, v216
	v_sub_f32_e32 v118, v118, v216
	v_sub_f32_e32 v119, v119, v216
	v_sub_f32_e32 v120, v120, v216
	v_sub_f32_e32 v121, v121, v216
	v_sub_f32_e32 v122, v122, v216
	v_sub_f32_e32 v123, v123, v216
	v_sub_f32_e32 v124, v124, v216
	v_sub_f32_e32 v125, v125, v216
	v_sub_f32_e32 v126, v126, v216
	v_sub_f32_e32 v127, v127, v216
	v_sub_f32_e32 v128, v128, v216
	v_sub_f32_e32 v129, v129, v216
	v_sub_f32_e32 v130, v130, v216
	v_sub_f32_e32 v131, v131, v216
	v_sub_f32_e32 v132, v132, v216
	v_sub_f32_e32 v133, v133, v216
	v_sub_f32_e32 v134, v134, v216
	v_sub_f32_e32 v135, v135, v216
	v_sub_f32_e32 v136, v136, v216
	v_sub_f32_e32 v137, v137, v216
	v_sub_f32_e32 v138, v138, v216
	v_sub_f32_e32 v139, v139, v216
	v_sub_f32_e32 v140, v140, v216
	v_sub_f32_e32 v141, v141, v216
	v_sub_f32_e32 v142, v142, v216
	v_sub_f32_e32 v143, v143, v216
	v_sub_f32_e32 v144, v144, v216
	v_sub_f32_e32 v145, v145, v216
	v_mul_f32_e32 v213, v213, v217
	v_mul_f32_e32 v214, v214, v217
	v_mul_f32_e32 v2, v2, v217
	v_mul_f32_e32 v3, v3, v217
	v_mul_f32_e32 v4, v4, v217
	v_mul_f32_e32 v5, v5, v217
	v_mul_f32_e32 v6, v6, v217
	v_mul_f32_e32 v7, v7, v217
	v_mul_f32_e32 v8, v8, v217
	v_mul_f32_e32 v9, v9, v217
	v_mul_f32_e32 v10, v10, v217
	v_mul_f32_e32 v11, v11, v217
	v_mul_f32_e32 v12, v12, v217
	v_mul_f32_e32 v13, v13, v217
	v_mul_f32_e32 v14, v14, v217
	v_mul_f32_e32 v15, v15, v217
	v_mul_f32_e32 v16, v16, v217
	v_mul_f32_e32 v17, v17, v217
	v_mul_f32_e32 v18, v18, v217
	v_mul_f32_e32 v19, v19, v217
	v_mul_f32_e32 v20, v20, v217
	v_mul_f32_e32 v21, v21, v217
	v_mul_f32_e32 v22, v22, v217
	v_mul_f32_e32 v23, v23, v217
	v_mul_f32_e32 v24, v24, v217
	v_mul_f32_e32 v25, v25, v217
	v_mul_f32_e32 v26, v26, v217
	v_mul_f32_e32 v27, v27, v217
	v_mul_f32_e32 v28, v28, v217
	v_mul_f32_e32 v29, v29, v217
	v_mul_f32_e32 v30, v30, v217
	v_mul_f32_e32 v31, v31, v217
	v_mul_f32_e32 v32, v32, v217
	v_mul_f32_e32 v33, v33, v217
.Lna_nr_c0:
	s_waitcnt lgkmcnt(0)
	s_barrier
	ds_read_b128 v[146:149], v200 offset:0
	ds_read_b128 v[150:153], v200 offset:4608
	ds_read_b128 v[154:157], v200 offset:32
	ds_read_b128 v[158:161], v200 offset:4640
	v_exp_f32_e32 v66, v66
	v_exp_f32_e32 v67, v67
	v_exp_f32_e32 v68, v68
	v_exp_f32_e32 v69, v69
	s_waitcnt lgkmcnt(2)
	v_mfma_f32_32x32x16_bf16 v[34:49], v[146:149], v[98:101], v[114:129]
	ds_read_b128 v[146:149], v200 offset:64
	v_add_f32_e32 v213, v213, v66
	v_add_f32_e32 v214, v214, v67
	v_add_f32_e32 v213, v213, v68
	v_add_f32_e32 v214, v214, v69
	v_exp_f32_e32 v70, v70
	v_exp_f32_e32 v71, v71
	v_mfma_f32_32x32x16_bf16 v[50:65], v[150:153], v[98:101], v[130:145]
	ds_read_b128 v[150:153], v200 offset:4672
	v_exp_f32_e32 v72, v72
	v_exp_f32_e32 v73, v73
	v_add_f32_e32 v213, v213, v70
	v_add_f32_e32 v214, v214, v71
	v_add_f32_e32 v213, v213, v72
	s_waitcnt lgkmcnt(2)
	v_mfma_f32_32x32x16_bf16 v[34:49], v[154:157], v[102:105], v[34:49]
	ds_read_b128 v[154:157], v200 offset:96
	v_add_f32_e32 v214, v214, v73
	v_cvt_pk_bf16_f32 v66, v66, v67
	v_cvt_pk_bf16_f32 v67, v68, v69
	v_cvt_pk_bf16_f32 v68, v70, v71
	v_cvt_pk_bf16_f32 v69, v72, v73
	v_exp_f32_e32 v74, v74
	v_exp_f32_e32 v75, v75
	v_mfma_f32_32x32x16_bf16 v[50:65], v[158:161], v[102:105], v[50:65]
	ds_read_b128 v[158:161], v200 offset:4704
	v_exp_f32_e32 v76, v76
	v_exp_f32_e32 v77, v77
	v_add_f32_e32 v213, v213, v74
	v_add_f32_e32 v214, v214, v75
	s_waitcnt lgkmcnt(2)
	v_mfma_f32_32x32x16_bf16 v[34:49], v[146:149], v[106:109], v[34:49]
	ds_read_b64 v[162:163], v202 offset:8704
	ds_read_b64 v[164:165], v202 offset:8720
	v_add_f32_e32 v213, v213, v76
	v_add_f32_e32 v214, v214, v77
	v_exp_f32_e32 v78, v78
	v_exp_f32_e32 v79, v79
	v_exp_f32_e32 v80, v80
	v_mfma_f32_32x32x16_bf16 v[50:65], v[150:153], v[106:109], v[50:65]
	ds_read_b64 v[166:167], v202 offset:13056
	ds_read_b64 v[168:169], v202 offset:13072
	v_exp_f32_e32 v81, v81
	v_add_f32_e32 v213, v213, v78
	v_add_f32_e32 v214, v214, v79
	v_add_f32_e32 v213, v213, v80
	v_add_f32_e32 v214, v214, v81
	v_cvt_pk_bf16_f32 v74, v74, v75
	v_cvt_pk_bf16_f32 v75, v76, v77
	s_waitcnt lgkmcnt(4)
	v_mfma_f32_32x32x16_bf16 v[34:49], v[154:157], v[110:113], v[34:49]
	ds_read_b64 v[170:171], v202 offset:8736
	ds_read_b64 v[172:173], v202 offset:8752
	v_cvt_pk_bf16_f32 v76, v78, v79
	v_cvt_pk_bf16_f32 v77, v80, v81
	v_exp_f32_e32 v82, v82
	v_exp_f32_e32 v83, v83
	v_exp_f32_e32 v84, v84
	v_mfma_f32_32x32x16_bf16 v[50:65], v[158:161], v[110:113], v[50:65]
	ds_read_b64 v[174:175], v202 offset:13088
	ds_read_b64 v[176:177], v202 offset:13104
	v_exp_f32_e32 v85, v85
	v_add_f32_e32 v213, v213, v82
	v_add_f32_e32 v214, v214, v83
	v_add_f32_e32 v213, v213, v84
	v_add_f32_e32 v214, v214, v85
	v_exp_f32_e32 v86, v86
	s_waitcnt lgkmcnt(6)
	v_mfma_f32_32x32x16_bf16 v[2:17], v[162:165], v[66:69], v[2:17]
	ds_read_b64 v[162:163], v202 offset:8768
	ds_read_b64 v[164:165], v202 offset:8784
	v_exp_f32_e32 v87, v87
	v_exp_f32_e32 v88, v88
	v_exp_f32_e32 v89, v89
	s_waitcnt lgkmcnt(6)
	v_mfma_f32_32x32x16_bf16 v[18:33], v[166:169], v[66:69], v[18:33]
	ds_read_b64 v[166:167], v202 offset:13120
	ds_read_b64 v[168:169], v202 offset:13136
	v_add_f32_e32 v213, v213, v86
	v_add_f32_e32 v214, v214, v87
	v_add_f32_e32 v213, v213, v88
	v_add_f32_e32 v214, v214, v89
	v_cvt_pk_bf16_f32 v82, v82, v83
	v_cvt_pk_bf16_f32 v83, v84, v85
	v_cvt_pk_bf16_f32 v84, v86, v87
	v_cvt_pk_bf16_f32 v85, v88, v89
	s_waitcnt lgkmcnt(6)
	v_mfma_f32_32x32x16_bf16 v[2:17], v[170:173], v[74:77], v[2:17]
	ds_read_b64 v[170:171], v202 offset:8800
	ds_read_b64 v[172:173], v202 offset:8816
	v_exp_f32_e32 v90, v90
	v_exp_f32_e32 v91, v91
	v_exp_f32_e32 v92, v92
	v_exp_f32_e32 v93, v93
	s_waitcnt lgkmcnt(6)
	v_mfma_f32_32x32x16_bf16 v[18:33], v[174:177], v[74:77], v[18:33]
	ds_read_b64 v[174:175], v202 offset:13152
	ds_read_b64 v[176:177], v202 offset:13168
	s_waitcnt vmcnt(1)
	ds_write_b128 v204, v[230:233] offset:9216
	ds_write_b64 v205, v[234:235] offset:0
	ds_write_b64 v205, v[236:237] offset:8
	v_add_f32_e32 v213, v213, v90
	v_add_f32_e32 v214, v214, v91
	v_add_f32_e32 v213, v213, v92
	v_add_f32_e32 v214, v214, v93
	v_exp_f32_e32 v94, v94
	v_exp_f32_e32 v95, v95
	s_waitcnt lgkmcnt(9)
	v_mfma_f32_32x32x16_bf16 v[2:17], v[162:165], v[82:85], v[2:17]
	v_exp_f32_e32 v96, v96
	v_exp_f32_e32 v97, v97
	v_add_f32_e32 v213, v213, v94
	v_add_f32_e32 v214, v214, v95
	v_add_f32_e32 v213, v213, v96
	s_waitcnt lgkmcnt(7)
	v_mfma_f32_32x32x16_bf16 v[18:33], v[166:169], v[82:85], v[18:33]
	v_add_f32_e32 v214, v214, v97
	v_cvt_pk_bf16_f32 v90, v90, v91
	v_cvt_pk_bf16_f32 v91, v92, v93
	v_cvt_pk_bf16_f32 v92, v94, v95
	v_cvt_pk_bf16_f32 v93, v96, v97
	v_max3_f32 v216, v34, v35, v36
	v_max3_f32 v216, v216, v37, v38
	s_waitcnt lgkmcnt(5)
	v_mfma_f32_32x32x16_bf16 v[2:17], v[170:173], v[90:93], v[2:17]
	v_max3_f32 v216, v216, v39, v40
	v_max3_f32 v216, v216, v41, v42
	v_max3_f32 v216, v216, v43, v44
	v_max3_f32 v216, v216, v45, v46
	v_max3_f32 v216, v216, v47, v48
	v_max3_f32 v216, v216, v49, v50
	v_max3_f32 v216, v216, v51, v52
	v_max3_f32 v216, v216, v53, v54
	s_waitcnt lgkmcnt(3)
	v_mfma_f32_32x32x16_bf16 v[18:33], v[174:177], v[90:93], v[18:33]
	v_max3_f32 v216, v216, v55, v56
	v_max3_f32 v216, v216, v57, v58
	v_max3_f32 v216, v216, v59, v60
	v_max3_f32 v216, v216, v61, v62
	v_max3_f32 v216, v216, v63, v64
	v_max_f32_e32 v216, v216, v65
	v_cmp_lt_f32_e32 vcc, 4.0, v216
	s_cbranch_vccz .Lna_nr_c1
	v_mov_b32_e32 v217, v216
	s_nop 1
	v_permlane32_swap_b32_e32 v216, v217
	v_max_f32_e32 v215, v216, v217
	s_nop 15
	v_max_f32_e32 v216, v215, v220
	v_exp_f32_e64 v217, -v216
	v_add_f32_e32 v212, v212, v216
	v_and_b32_e32 v217, v217, v221
	v_sub_f32_e32 v34, v34, v216
	v_sub_f32_e32 v35, v35, v216
	v_sub_f32_e32 v36, v36, v216
	v_sub_f32_e32 v37, v37, v216
	v_sub_f32_e32 v38, v38, v216
	v_sub_f32_e32 v39, v39, v216
	v_sub_f32_e32 v40, v40, v216
	v_sub_f32_e32 v41, v41, v216
	v_sub_f32_e32 v42, v42, v216
	v_sub_f32_e32 v43, v43, v216
	v_sub_f32_e32 v44, v44, v216
	v_sub_f32_e32 v45, v45, v216
	v_sub_f32_e32 v46, v46, v216
	v_sub_f32_e32 v47, v47, v216
	v_sub_f32_e32 v48, v48, v216
	v_sub_f32_e32 v49, v49, v216
	v_sub_f32_e32 v50, v50, v216
	v_sub_f32_e32 v51, v51, v216
	v_sub_f32_e32 v52, v52, v216
	v_sub_f32_e32 v53, v53, v216
	v_sub_f32_e32 v54, v54, v216
	v_sub_f32_e32 v55, v55, v216
	v_sub_f32_e32 v56, v56, v216
	v_sub_f32_e32 v57, v57, v216
	v_sub_f32_e32 v58, v58, v216
	v_sub_f32_e32 v59, v59, v216
	v_sub_f32_e32 v60, v60, v216
	v_sub_f32_e32 v61, v61, v216
	v_sub_f32_e32 v62, v62, v216
	v_sub_f32_e32 v63, v63, v216
	v_sub_f32_e32 v64, v64, v216
	v_sub_f32_e32 v65, v65, v216
	v_sub_f32_e32 v114, v114, v216
	v_sub_f32_e32 v115, v115, v216
	v_sub_f32_e32 v116, v116, v216
	v_sub_f32_e32 v117, v117, v216
	v_sub_f32_e32 v118, v118, v216
	v_sub_f32_e32 v119, v119, v216
	v_sub_f32_e32 v120, v120, v216
	v_sub_f32_e32 v121, v121, v216
	v_sub_f32_e32 v122, v122, v216
	v_sub_f32_e32 v123, v123, v216
	v_sub_f32_e32 v124, v124, v216
	v_sub_f32_e32 v125, v125, v216
	v_sub_f32_e32 v126, v126, v216
	v_sub_f32_e32 v127, v127, v216
	v_sub_f32_e32 v128, v128, v216
	v_sub_f32_e32 v129, v129, v216
	v_sub_f32_e32 v130, v130, v216
	v_sub_f32_e32 v131, v131, v216
	v_sub_f32_e32 v132, v132, v216
	v_sub_f32_e32 v133, v133, v216
	v_sub_f32_e32 v134, v134, v216
	v_sub_f32_e32 v135, v135, v216
	v_sub_f32_e32 v136, v136, v216
	v_sub_f32_e32 v137, v137, v216
	v_sub_f32_e32 v138, v138, v216
	v_sub_f32_e32 v139, v139, v216
	v_sub_f32_e32 v140, v140, v216
	v_sub_f32_e32 v141, v141, v216
	v_sub_f32_e32 v142, v142, v216
	v_sub_f32_e32 v143, v143, v216
	v_sub_f32_e32 v144, v144, v216
	v_sub_f32_e32 v145, v145, v216
	v_mul_f32_e32 v213, v213, v217
	v_mul_f32_e32 v214, v214, v217
	v_mul_f32_e32 v2, v2, v217
	v_mul_f32_e32 v3, v3, v217
	v_mul_f32_e32 v4, v4, v217
	v_mul_f32_e32 v5, v5, v217
	v_mul_f32_e32 v6, v6, v217
	v_mul_f32_e32 v7, v7, v217
	v_mul_f32_e32 v8, v8, v217
	v_mul_f32_e32 v9, v9, v217
	v_mul_f32_e32 v10, v10, v217
	v_mul_f32_e32 v11, v11, v217
	v_mul_f32_e32 v12, v12, v217
	v_mul_f32_e32 v13, v13, v217
	v_mul_f32_e32 v14, v14, v217
	v_mul_f32_e32 v15, v15, v217
	v_mul_f32_e32 v16, v16, v217
	v_mul_f32_e32 v17, v17, v217
	v_mul_f32_e32 v18, v18, v217
	v_mul_f32_e32 v19, v19, v217
	v_mul_f32_e32 v20, v20, v217
	v_mul_f32_e32 v21, v21, v217
	v_mul_f32_e32 v22, v22, v217
	v_mul_f32_e32 v23, v23, v217
	v_mul_f32_e32 v24, v24, v217
	v_mul_f32_e32 v25, v25, v217
	v_mul_f32_e32 v26, v26, v217
	v_mul_f32_e32 v27, v27, v217
	v_mul_f32_e32 v28, v28, v217
	v_mul_f32_e32 v29, v29, v217
	v_mul_f32_e32 v30, v30, v217
	v_mul_f32_e32 v31, v31, v217
	v_mul_f32_e32 v32, v32, v217
	v_mul_f32_e32 v33, v33, v217
.Lna_nr_c1:
	s_waitcnt lgkmcnt(0)
	s_barrier
	ds_read_b128 v[146:149], v200 offset:9216
	ds_read_b128 v[150:153], v200 offset:13824
	ds_read_b128 v[154:157], v200 offset:9248
	ds_read_b128 v[158:161], v200 offset:13856
	v_exp_f32_e32 v34, v34
	v_exp_f32_e32 v35, v35
	v_exp_f32_e32 v36, v36
	v_exp_f32_e32 v37, v37
	s_waitcnt lgkmcnt(2)
	v_mfma_f32_32x32x16_bf16 v[66:81], v[146:149], v[98:101], v[114:129]
	ds_read_b128 v[146:149], v200 offset:9280
	v_add_f32_e32 v213, v213, v34
	v_add_f32_e32 v214, v214, v35
	v_add_f32_e32 v213, v213, v36
	v_add_f32_e32 v214, v214, v37
	v_exp_f32_e32 v38, v38
	v_exp_f32_e32 v39, v39
	v_mfma_f32_32x32x16_bf16 v[82:97], v[150:153], v[98:101], v[130:145]
	ds_read_b128 v[150:153], v200 offset:13888
	v_exp_f32_e32 v40, v40
	v_exp_f32_e32 v41, v41
	v_add_f32_e32 v213, v213, v38
	v_add_f32_e32 v214, v214, v39
	v_add_f32_e32 v213, v213, v40
	s_waitcnt lgkmcnt(2)
	v_mfma_f32_32x32x16_bf16 v[66:81], v[154:157], v[102:105], v[66:81]
	ds_read_b128 v[154:157], v200 offset:9312
	v_add_f32_e32 v214, v214, v41
	v_cvt_pk_bf16_f32 v34, v34, v35
	v_cvt_pk_bf16_f32 v35, v36, v37
	v_cvt_pk_bf16_f32 v36, v38, v39
	v_cvt_pk_bf16_f32 v37, v40, v41
	v_exp_f32_e32 v42, v42
	v_exp_f32_e32 v43, v43
	v_mfma_f32_32x32x16_bf16 v[82:97], v[158:161], v[102:105], v[82:97]
	ds_read_b128 v[158:161], v200 offset:13920
	v_exp_f32_e32 v44, v44
	v_exp_f32_e32 v45, v45
	v_add_f32_e32 v213, v213, v42
	v_add_f32_e32 v214, v214, v43
	s_waitcnt lgkmcnt(2)
	v_mfma_f32_32x32x16_bf16 v[66:81], v[146:149], v[106:109], v[66:81]
	ds_read_b64 v[162:163], v202 offset:0
	ds_read_b64 v[164:165], v202 offset:16
	v_add_f32_e32 v213, v213, v44
	v_add_f32_e32 v214, v214, v45
	v_exp_f32_e32 v46, v46
	v_exp_f32_e32 v47, v47
	v_exp_f32_e32 v48, v48
	v_mfma_f32_32x32x16_bf16 v[82:97], v[150:153], v[106:109], v[82:97]
	ds_read_b64 v[166:167], v202 offset:4352
	ds_read_b64 v[168:169], v202 offset:4368
	v_exp_f32_e32 v49, v49
	v_add_f32_e32 v213, v213, v46
	v_add_f32_e32 v214, v214, v47
	v_add_f32_e32 v213, v213, v48
	v_add_f32_e32 v214, v214, v49
	v_cvt_pk_bf16_f32 v42, v42, v43
	v_cvt_pk_bf16_f32 v43, v44, v45
	s_waitcnt lgkmcnt(4)
	v_mfma_f32_32x32x16_bf16 v[66:81], v[154:157], v[110:113], v[66:81]
	ds_read_b64 v[170:171], v202 offset:32
	ds_read_b64 v[172:173], v202 offset:48
	v_cvt_pk_bf16_f32 v44, v46, v47
	v_cvt_pk_bf16_f32 v45, v48, v49
	v_exp_f32_e32 v50, v50
	v_exp_f32_e32 v51, v51
	v_exp_f32_e32 v52, v52
	v_mfma_f32_32x32x16_bf16 v[82:97], v[158:161], v[110:113], v[82:97]
	ds_read_b64 v[174:175], v202 offset:4384
	ds_read_b64 v[176:177], v202 offset:4400
	v_exp_f32_e32 v53, v53
	v_add_f32_e32 v213, v213, v50
	v_add_f32_e32 v214, v214, v51
	v_add_f32_e32 v213, v213, v52
	v_add_f32_e32 v214, v214, v53
	v_exp_f32_e32 v54, v54
	s_waitcnt lgkmcnt(6)
	v_mfma_f32_32x32x16_bf16 v[2:17], v[162:165], v[34:37], v[2:17]
	ds_read_b64 v[162:163], v202 offset:64
	ds_read_b64 v[164:165], v202 offset:80
	v_exp_f32_e32 v55, v55
	v_exp_f32_e32 v56, v56
	v_exp_f32_e32 v57, v57
	s_waitcnt lgkmcnt(6)
	v_mfma_f32_32x32x16_bf16 v[18:33], v[166:169], v[34:37], v[18:33]
	ds_read_b64 v[166:167], v202 offset:4416
	ds_read_b64 v[168:169], v202 offset:4432
	v_add_f32_e32 v213, v213, v54
	v_add_f32_e32 v214, v214, v55
	v_add_f32_e32 v213, v213, v56
	v_add_f32_e32 v214, v214, v57
	v_cvt_pk_bf16_f32 v50, v50, v51
	v_cvt_pk_bf16_f32 v51, v52, v53
	v_cvt_pk_bf16_f32 v52, v54, v55
	v_cvt_pk_bf16_f32 v53, v56, v57
	s_waitcnt lgkmcnt(6)
	v_mfma_f32_32x32x16_bf16 v[2:17], v[170:173], v[42:45], v[2:17]
	ds_read_b64 v[170:171], v202 offset:96
	ds_read_b64 v[172:173], v202 offset:112
	v_exp_f32_e32 v58, v58
	v_exp_f32_e32 v59, v59
	v_exp_f32_e32 v60, v60
	v_exp_f32_e32 v61, v61
	s_waitcnt lgkmcnt(6)
	v_mfma_f32_32x32x16_bf16 v[18:33], v[174:177], v[42:45], v[18:33]
	ds_read_b64 v[174:175], v202 offset:4448
	ds_read_b64 v[176:177], v202 offset:4464
	s_waitcnt vmcnt(0)
	ds_write_b64 v205, v[192:193] offset:8704
	ds_write_b64 v205, v[194:195] offset:8712
	v_add_f32_e32 v213, v213, v58
	v_add_f32_e32 v214, v214, v59
	v_add_f32_e32 v213, v213, v60
	v_add_f32_e32 v214, v214, v61
	v_exp_f32_e32 v62, v62
	v_exp_f32_e32 v63, v63
	s_waitcnt lgkmcnt(8)
	v_mfma_f32_32x32x16_bf16 v[2:17], v[162:165], v[50:53], v[2:17]
	v_exp_f32_e32 v64, v64
	v_exp_f32_e32 v65, v65
	v_add_f32_e32 v213, v213, v62
	v_add_f32_e32 v214, v214, v63
	v_add_f32_e32 v213, v213, v64
	s_waitcnt lgkmcnt(6)
	v_mfma_f32_32x32x16_bf16 v[18:33], v[166:169], v[50:53], v[18:33]
	v_add_f32_e32 v214, v214, v65
	v_cvt_pk_bf16_f32 v58, v58, v59
	v_cvt_pk_bf16_f32 v59, v60, v61
	v_cvt_pk_bf16_f32 v60, v62, v63
	v_cvt_pk_bf16_f32 v61, v64, v65
	v_max3_f32 v216, v66, v67, v68
	v_max3_f32 v216, v216, v69, v70
	s_waitcnt lgkmcnt(4)
	v_mfma_f32_32x32x16_bf16 v[2:17], v[170:173], v[58:61], v[2:17]
	v_max3_f32 v216, v216, v71, v72
	v_max3_f32 v216, v216, v73, v74
	v_max3_f32 v216, v216, v75, v76
	v_max3_f32 v216, v216, v77, v78
	v_max3_f32 v216, v216, v79, v80
	v_max3_f32 v216, v216, v81, v82
	v_max3_f32 v216, v216, v83, v84
	v_max3_f32 v216, v216, v85, v86
	s_waitcnt lgkmcnt(2)
	v_mfma_f32_32x32x16_bf16 v[18:33], v[174:177], v[58:61], v[18:33]
	v_max3_f32 v216, v216, v87, v88
	v_max3_f32 v216, v216, v89, v90
	v_max3_f32 v216, v216, v91, v92
	v_max3_f32 v216, v216, v93, v94
	v_max3_f32 v216, v216, v95, v96
	v_max_f32_e32 v216, v216, v97
	v_cmp_lt_f32_e32 vcc, 4.0, v216
	s_cbranch_vccz .Lna_nr_c2
	v_mov_b32_e32 v217, v216
	s_nop 1
	v_permlane32_swap_b32_e32 v216, v217
	v_max_f32_e32 v215, v216, v217
	s_nop 15
	v_max_f32_e32 v216, v215, v220
	v_exp_f32_e64 v217, -v216
	v_add_f32_e32 v212, v212, v216
	v_and_b32_e32 v217, v217, v221
	v_sub_f32_e32 v66, v66, v216
	v_sub_f32_e32 v67, v67, v216
	v_sub_f32_e32 v68, v68, v216
	v_sub_f32_e32 v69, v69, v216
	v_sub_f32_e32 v70, v70, v216
	v_sub_f32_e32 v71, v71, v216
	v_sub_f32_e32 v72, v72, v216
	v_sub_f32_e32 v73, v73, v216
	v_sub_f32_e32 v74, v74, v216
	v_sub_f32_e32 v75, v75, v216
	v_sub_f32_e32 v76, v76, v216
	v_sub_f32_e32 v77, v77, v216
	v_sub_f32_e32 v78, v78, v216
	v_sub_f32_e32 v79, v79, v216
	v_sub_f32_e32 v80, v80, v216
	v_sub_f32_e32 v81, v81, v216
	v_sub_f32_e32 v82, v82, v216
	v_sub_f32_e32 v83, v83, v216
	v_sub_f32_e32 v84, v84, v216
	v_sub_f32_e32 v85, v85, v216
	v_sub_f32_e32 v86, v86, v216
	v_sub_f32_e32 v87, v87, v216
	v_sub_f32_e32 v88, v88, v216
	v_sub_f32_e32 v89, v89, v216
	v_sub_f32_e32 v90, v90, v216
	v_sub_f32_e32 v91, v91, v216
	v_sub_f32_e32 v92, v92, v216
	v_sub_f32_e32 v93, v93, v216
	v_sub_f32_e32 v94, v94, v216
	v_sub_f32_e32 v95, v95, v216
	v_sub_f32_e32 v96, v96, v216
	v_sub_f32_e32 v97, v97, v216
	v_sub_f32_e32 v114, v114, v216
	v_sub_f32_e32 v115, v115, v216
	v_sub_f32_e32 v116, v116, v216
	v_sub_f32_e32 v117, v117, v216
	v_sub_f32_e32 v118, v118, v216
	v_sub_f32_e32 v119, v119, v216
	v_sub_f32_e32 v120, v120, v216
	v_sub_f32_e32 v121, v121, v216
	v_sub_f32_e32 v122, v122, v216
	v_sub_f32_e32 v123, v123, v216
	v_sub_f32_e32 v124, v124, v216
	v_sub_f32_e32 v125, v125, v216
	v_sub_f32_e32 v126, v126, v216
	v_sub_f32_e32 v127, v127, v216
	v_sub_f32_e32 v128, v128, v216
	v_sub_f32_e32 v129, v129, v216
	v_sub_f32_e32 v130, v130, v216
	v_sub_f32_e32 v131, v131, v216
	v_sub_f32_e32 v132, v132, v216
	v_sub_f32_e32 v133, v133, v216
	v_sub_f32_e32 v134, v134, v216
	v_sub_f32_e32 v135, v135, v216
	v_sub_f32_e32 v136, v136, v216
	v_sub_f32_e32 v137, v137, v216
	v_sub_f32_e32 v138, v138, v216
	v_sub_f32_e32 v139, v139, v216
	v_sub_f32_e32 v140, v140, v216
	v_sub_f32_e32 v141, v141, v216
	v_sub_f32_e32 v142, v142, v216
	v_sub_f32_e32 v143, v143, v216
	v_sub_f32_e32 v144, v144, v216
	v_sub_f32_e32 v145, v145, v216
	v_mul_f32_e32 v213, v213, v217
	v_mul_f32_e32 v214, v214, v217
	v_mul_f32_e32 v2, v2, v217
	v_mul_f32_e32 v3, v3, v217
	v_mul_f32_e32 v4, v4, v217
	v_mul_f32_e32 v5, v5, v217
	v_mul_f32_e32 v6, v6, v217
	v_mul_f32_e32 v7, v7, v217
	v_mul_f32_e32 v8, v8, v217
	v_mul_f32_e32 v9, v9, v217
	v_mul_f32_e32 v10, v10, v217
	v_mul_f32_e32 v11, v11, v217
	v_mul_f32_e32 v12, v12, v217
	v_mul_f32_e32 v13, v13, v217
	v_mul_f32_e32 v14, v14, v217
	v_mul_f32_e32 v15, v15, v217
	v_mul_f32_e32 v16, v16, v217
	v_mul_f32_e32 v17, v17, v217
	v_mul_f32_e32 v18, v18, v217
	v_mul_f32_e32 v19, v19, v217
	v_mul_f32_e32 v20, v20, v217
	v_mul_f32_e32 v21, v21, v217
	v_mul_f32_e32 v22, v22, v217
	v_mul_f32_e32 v23, v23, v217
	v_mul_f32_e32 v24, v24, v217
	v_mul_f32_e32 v25, v25, v217
	v_mul_f32_e32 v26, v26, v217
	v_mul_f32_e32 v27, v27, v217
	v_mul_f32_e32 v28, v28, v217
	v_mul_f32_e32 v29, v29, v217
	v_mul_f32_e32 v30, v30, v217
	v_mul_f32_e32 v31, v31, v217
	v_mul_f32_e32 v32, v32, v217
	v_mul_f32_e32 v33, v33, v217
